# attention epilogues: lane-xor-1 exchange via DPP quad_perm instead of ds_bpermute round trips (on top of wait cleanup edits)
# speedup vs baseline: 1.0099x; 1.0099x over previous
; __device__ __forceinline__ unsigned cvt_pk_bf16(float lo, float hi) { unsigned r; asm volatile("v_cvt_pk_bf16_f32 %0, %1, %2" : "=v"(r) : "v"(lo), "v"(hi)); return r; }
; __device__ __forceinline__ int crow(int r, int hi) { return (r & 3) + 8 * (r >> 2) + 4 * hi; }
; template <int MODE, bool SAMPLE>
; __device__ __forceinline__ void unit(LAS char* lds, const UnitDesc& D) {
;     ...
;     if (wact) {
;         float rli[16];
;         if (MODE == 0) { if (hi == 0) ws[32 + r32] = l_reg; asm volatile("s_waitcnt lgkmcnt(0)" ::: "memory");
; #pragma unroll
;             for (int r = 0; r < 16; ++r) rli[r] = __builtin_amdgcn_rcpf(ws[32 + crow(r, hi)]); }
;         bf16* Ow = D.O + (size_t)(wid * 32) * DM;
; #pragma unroll
;         for (int r = 0; r < 16; ++r) { const int orow = crow(r, hi);
; #pragma unroll
;             for (int d0 = 0; d0 < 4; ++d0) { const float v = MODE == 0 ? o[d0][r] * rli[r] : o[d0][r];
;                 const float vn = __shfl_xor(v, 1);
;                 if ((r32 & 1) == 0 && wid * 32 + orow < D.nq) *(unsigned*)(Ow + (size_t)orow * DM + d0 * 32 + r32) = cvt_pk_bf16(v, vn); } }
.LBB0_850:
	s_andn2_b64 vcc, exec, s[38:39]
	s_cbranch_vccnz .LBB0_818
	s_and_saveexec_b64 s[4:5], s[8:9]
	ds_write_b32 v170, v181 offset:128
	s_or_b64 exec, exec, s[4:5]
	s_waitcnt lgkmcnt(0)
	v_add_u32_e32 v2, s16, v150
	ds_read_b128 v[80:83], v2 offset:128
	ds_read_b128 v[76:79], v2 offset:160
	s_lshl_b64 s[4:5], s[34:35], 1
	s_add_u32 s2, s30, s4
	s_addc_u32 s4, s31, s5
	s_waitcnt lgkmcnt(1)
	v_rcp_f32_e32 v88, v80
	v_and_b32_e32 v80, 64, v158
	s_lshl_b32 s3, s3, 1
	ds_read_b128 v[72:75], v2 offset:192
	ds_read_b128 v[68:71], v2 offset:224
	v_xor_b32_e32 v2, 1, v158
	v_add_u32_e32 v80, 64, v80
	s_add_u32 s5, s2, s3
	v_cmp_lt_i32_e32 vcc, v2, v80
	s_addc_u32 s4, s4, 0
	s_ashr_i32 s29, s28, 31
	v_cndmask_b32_e32 v2, v158, v2, vcc
	s_lshl_b64 s[2:3], s[28:29], 12
	v_lshlrev_b32_e32 v80, 2, v2
	v_mul_f32_e32 v52, v52, v88
	s_add_u32 s2, s5, s2
	v_and_b32_e32 v2, 1, v160
	s_nop 1
	v_mov_b32_dpp v89, v52 quad_perm:[1,0,3,2] row_mask:0xf bank_mask:0xf
	s_addc_u32 s3, s4, s3
	v_cmp_eq_u32_e32 vcc, 0, v2
	v_lshlrev_b32_e32 v2, 1, v161
	v_lshl_add_u64 v[84:85], s[2:3], 0, v[2:3]
	v_or_b32_e32 v90, s28, v151
	v_lshl_add_u64 v[84:85], v[84:85], 0, s[26:27]
	v_lshlrev_b32_e32 v2, 14, v159
	v_cmp_gt_i32_e64 s[6:7], s23, v90
	v_lshl_add_u64 v[86:87], v[84:85], 0, v[2:3]
	s_and_b64 s[4:5], vcc, s[6:7]
	s_and_saveexec_b64 s[6:7], s[4:5]
	s_cbranch_execz .LBB0_855
	s_waitcnt lgkmcnt(0)
	v_cvt_pk_bf16_f32 v2, v52, v89
	global_store_dword v[86:87], v2, off
.LBB0_855:
	s_or_b64 exec, exec, s[6:7]
	v_mul_f32_e32 v2, v36, v88
	s_nop 1
	v_mov_b32_dpp v36, v2 quad_perm:[1,0,3,2] row_mask:0xf bank_mask:0xf
	s_and_saveexec_b64 s[6:7], s[4:5]
	s_cbranch_execz .LBB0_857
	s_waitcnt lgkmcnt(0)
	v_cvt_pk_bf16_f32 v2, v2, v36
	global_store_dword v[86:87], v2, off offset:64
.LBB0_857:
	s_or_b64 exec, exec, s[6:7]
	v_mul_f32_e32 v2, v20, v88
	s_nop 1
	v_mov_b32_dpp v20, v2 quad_perm:[1,0,3,2] row_mask:0xf bank_mask:0xf
	s_and_saveexec_b64 s[6:7], s[4:5]
	s_cbranch_execz .LBB0_859
	s_waitcnt lgkmcnt(0)
	v_cvt_pk_bf16_f32 v2, v2, v20
	global_store_dword v[86:87], v2, off offset:128
.LBB0_859:
	s_or_b64 exec, exec, s[6:7]
	v_mul_f32_e32 v2, v4, v88
	s_nop 1
	v_mov_b32_dpp v4, v2 quad_perm:[1,0,3,2] row_mask:0xf bank_mask:0xf
	s_and_saveexec_b64 s[6:7], s[4:5]
	s_cbranch_execz .LBB0_861
	s_waitcnt lgkmcnt(0)
	v_cvt_pk_bf16_f32 v2, v2, v4
	global_store_dword v[86:87], v2, off offset:192
.LBB0_861:
	s_or_b64 exec, exec, s[6:7]
	s_waitcnt lgkmcnt(0)
	v_rcp_f32_e32 v4, v81
	v_or_b32_e32 v2, 1, v151
	v_or_b32_e32 v81, s28, v2
	v_lshlrev_b32_e32 v2, 12, v2
	v_mul_f32_e32 v20, v53, v4
	s_nop 1
	v_mov_b32_dpp v36, v20 quad_perm:[1,0,3,2] row_mask:0xf bank_mask:0xf
	v_cmp_gt_i32_e64 s[6:7], s23, v81
	v_lshl_add_u64 v[52:53], v[84:85], 0, v[2:3]
	s_and_b64 s[4:5], vcc, s[6:7]
	s_and_saveexec_b64 s[6:7], s[4:5]
	s_cbranch_execz .LBB0_863
	s_waitcnt lgkmcnt(0)
	v_cvt_pk_bf16_f32 v2, v20, v36
	global_store_dword v[52:53], v2, off
.LBB0_863:
	s_or_b64 exec, exec, s[6:7]
	v_mul_f32_e32 v2, v37, v4
	s_nop 1
	v_mov_b32_dpp v20, v2 quad_perm:[1,0,3,2] row_mask:0xf bank_mask:0xf
	s_and_saveexec_b64 s[6:7], s[4:5]
	s_cbranch_execz .LBB0_865
	s_waitcnt lgkmcnt(0)
	v_cvt_pk_bf16_f32 v2, v2, v20
	global_store_dword v[52:53], v2, off offset:64
.LBB0_865:
	s_or_b64 exec, exec, s[6:7]
	v_mul_f32_e32 v2, v21, v4
	s_waitcnt lgkmcnt(0)
	s_nop 1
	v_mov_b32_dpp v20, v2 quad_perm:[1,0,3,2] row_mask:0xf bank_mask:0xf
	s_and_saveexec_b64 s[6:7], s[4:5]
	s_cbranch_execz .LBB0_867
	s_waitcnt lgkmcnt(0)
	v_cvt_pk_bf16_f32 v2, v2, v20
	global_store_dword v[52:53], v2, off offset:128
.LBB0_867:
	s_or_b64 exec, exec, s[6:7]
	v_mul_f32_e32 v2, v5, v4
	s_nop 1
	v_mov_b32_dpp v4, v2 quad_perm:[1,0,3,2] row_mask:0xf bank_mask:0xf
	s_and_saveexec_b64 s[6:7], s[4:5]
	s_cbranch_execz .LBB0_869
	s_waitcnt lgkmcnt(0)
	v_cvt_pk_bf16_f32 v2, v2, v4
	global_store_dword v[52:53], v2, off offset:192
.LBB0_869:
	s_or_b64 exec, exec, s[6:7]
	s_waitcnt lgkmcnt(0)
	v_rcp_f32_e32 v20, v82
	v_or_b32_e32 v2, 2, v151
	v_or_b32_e32 v37, s28, v2
	v_lshlrev_b32_e32 v2, 12, v2
	v_mul_f32_e32 v21, v54, v20
	s_nop 1
	v_mov_b32_dpp v36, v21 quad_perm:[1,0,3,2] row_mask:0xf bank_mask:0xf
	v_cmp_gt_i32_e64 s[6:7], s23, v37
	s_waitcnt lgkmcnt(0)
	v_lshl_add_u64 v[4:5], v[84:85], 0, v[2:3]
	s_and_b64 s[4:5], vcc, s[6:7]
	s_and_saveexec_b64 s[6:7], s[4:5]
	s_cbranch_execz .LBB0_871
	s_waitcnt lgkmcnt(0)
	v_cvt_pk_bf16_f32 v2, v21, v36
	global_store_dword v[4:5], v2, off
.LBB0_871:
	s_or_b64 exec, exec, s[6:7]
	v_mul_f32_e32 v2, v38, v20
	s_nop 1
	v_mov_b32_dpp v21, v2 quad_perm:[1,0,3,2] row_mask:0xf bank_mask:0xf
	s_and_saveexec_b64 s[6:7], s[4:5]
	s_cbranch_execz .LBB0_873
	s_waitcnt lgkmcnt(0)
	v_cvt_pk_bf16_f32 v2, v2, v21
	global_store_dword v[4:5], v2, off offset:64
.LBB0_873:
	s_or_b64 exec, exec, s[6:7]
	v_mul_f32_e32 v2, v22, v20
	s_waitcnt lgkmcnt(0)
	s_nop 1
	v_mov_b32_dpp v21, v2 quad_perm:[1,0,3,2] row_mask:0xf bank_mask:0xf
	s_and_saveexec_b64 s[6:7], s[4:5]
	s_cbranch_execz .LBB0_875
	s_waitcnt lgkmcnt(0)
	v_cvt_pk_bf16_f32 v2, v2, v21
	global_store_dword v[4:5], v2, off offset:128
.LBB0_875:
	s_or_b64 exec, exec, s[6:7]
	v_mul_f32_e32 v2, v6, v20
	s_nop 1
	v_mov_b32_dpp v6, v2 quad_perm:[1,0,3,2] row_mask:0xf bank_mask:0xf
	s_and_saveexec_b64 s[6:7], s[4:5]
	s_cbranch_execz .LBB0_877
	s_waitcnt lgkmcnt(0)
	v_cvt_pk_bf16_f32 v2, v2, v6
	global_store_dword v[4:5], v2, off offset:192
; __device__ __forceinline__ unsigned cvt_pk_bf16(float lo, float hi) { unsigned r; asm volatile("v_cvt_pk_bf16_f32 %0, %1, %2" : "=v"(r) : "v"(lo), "v"(hi)); return r; }
; __device__ __forceinline__ int crow(int r, int hi) { return (r & 3) + 8 * (r >> 2) + 4 * hi; }
; template <int MODE, bool SAMPLE>
; __device__ __forceinline__ void unit(LAS char* lds, const UnitDesc& D) {
;     ...
;     if (wact) {
;         float rli[16];
;         if (MODE == 0) { if (hi == 0) ws[32 + r32] = l_reg; asm volatile("s_waitcnt lgkmcnt(0)" ::: "memory");
; #pragma unroll
;             for (int r = 0; r < 16; ++r) rli[r] = __builtin_amdgcn_rcpf(ws[32 + crow(r, hi)]); }
;         bf16* Ow = D.O + (size_t)(wid * 32) * DM;
; #pragma unroll
;         for (int r = 0; r < 16; ++r) { const int orow = crow(r, hi);
; #pragma unroll
;             for (int d0 = 0; d0 < 4; ++d0) { const float v = MODE == 0 ? o[d0][r] * rli[r] : o[d0][r];
;                 const float vn = __shfl_xor(v, 1);
;                 if ((r32 & 1) == 0 && wid * 32 + orow < D.nq) *(unsigned*)(Ow + (size_t)orow * DM + d0 * 32 + r32) = cvt_pk_bf16(v, vn); } }
.LBB0_877:
	s_or_b64 exec, exec, s[6:7]
	s_waitcnt lgkmcnt(0)
	v_rcp_f32_e32 v6, v83
	v_or_b32_e32 v2, 3, v151
	v_or_b32_e32 v22, s28, v2
	v_lshlrev_b32_e32 v2, 12, v2
	v_mul_f32_e32 v20, v55, v6
	s_nop 1
	v_mov_b32_dpp v21, v20 quad_perm:[1,0,3,2] row_mask:0xf bank_mask:0xf
	v_cmp_gt_i32_e64 s[6:7], s23, v22
	v_lshl_add_u64 v[4:5], v[84:85], 0, v[2:3]
	s_and_b64 s[4:5], vcc, s[6:7]
	s_and_saveexec_b64 s[6:7], s[4:5]
	s_cbranch_execz .LBB0_879
	s_waitcnt lgkmcnt(0)
	v_cvt_pk_bf16_f32 v2, v20, v21
	global_store_dword v[4:5], v2, off
.LBB0_879:
	s_or_b64 exec, exec, s[6:7]
	v_mul_f32_e32 v2, v39, v6
	s_nop 1
	v_mov_b32_dpp v20, v2 quad_perm:[1,0,3,2] row_mask:0xf bank_mask:0xf
	s_and_saveexec_b64 s[6:7], s[4:5]
	s_cbranch_execz .LBB0_881
	s_waitcnt lgkmcnt(0)
	v_cvt_pk_bf16_f32 v2, v2, v20
	global_store_dword v[4:5], v2, off offset:64
.LBB0_881:
	s_or_b64 exec, exec, s[6:7]
	v_mul_f32_e32 v2, v23, v6
	s_waitcnt lgkmcnt(0)
	s_nop 1
	v_mov_b32_dpp v20, v2 quad_perm:[1,0,3,2] row_mask:0xf bank_mask:0xf
	s_and_saveexec_b64 s[6:7], s[4:5]
	s_cbranch_execz .LBB0_883
	s_waitcnt lgkmcnt(0)
	v_cvt_pk_bf16_f32 v2, v2, v20
	global_store_dword v[4:5], v2, off offset:128
.LBB0_883:
	s_or_b64 exec, exec, s[6:7]
	v_mul_f32_e32 v2, v7, v6
	s_nop 1
	v_mov_b32_dpp v6, v2 quad_perm:[1,0,3,2] row_mask:0xf bank_mask:0xf
	s_and_saveexec_b64 s[6:7], s[4:5]
	s_cbranch_execz .LBB0_885
	s_waitcnt lgkmcnt(0)
	v_cvt_pk_bf16_f32 v2, v2, v6
	global_store_dword v[4:5], v2, off offset:192
.LBB0_885:
	s_or_b64 exec, exec, s[6:7]
	s_waitcnt lgkmcnt(0)
	v_rcp_f32_e32 v6, v76
	v_or_b32_e32 v2, 8, v151
	v_or_b32_e32 v21, s28, v2
	v_lshlrev_b32_e32 v2, 12, v2
	v_mul_f32_e32 v7, v56, v6
	s_nop 1
	v_mov_b32_dpp v20, v7 quad_perm:[1,0,3,2] row_mask:0xf bank_mask:0xf
	v_cmp_gt_i32_e64 s[6:7], s23, v21
	v_lshl_add_u64 v[4:5], v[84:85], 0, v[2:3]
	s_and_b64 s[4:5], vcc, s[6:7]
	s_and_saveexec_b64 s[6:7], s[4:5]
	s_cbranch_execz .LBB0_887
	s_waitcnt lgkmcnt(0)
	v_cvt_pk_bf16_f32 v2, v7, v20
	global_store_dword v[4:5], v2, off
.LBB0_887:
	s_or_b64 exec, exec, s[6:7]
	v_mul_f32_e32 v2, v40, v6
	s_nop 1
	v_mov_b32_dpp v7, v2 quad_perm:[1,0,3,2] row_mask:0xf bank_mask:0xf
	s_and_saveexec_b64 s[6:7], s[4:5]
	s_cbranch_execz .LBB0_889
	s_waitcnt lgkmcnt(0)
	v_cvt_pk_bf16_f32 v2, v2, v7
	global_store_dword v[4:5], v2, off offset:64
.LBB0_889:
	s_or_b64 exec, exec, s[6:7]
	v_mul_f32_e32 v2, v24, v6
	s_waitcnt lgkmcnt(0)
	s_nop 1
	v_mov_b32_dpp v7, v2 quad_perm:[1,0,3,2] row_mask:0xf bank_mask:0xf
	s_and_saveexec_b64 s[6:7], s[4:5]
	s_cbranch_execz .LBB0_891
	s_waitcnt lgkmcnt(0)
	v_cvt_pk_bf16_f32 v2, v2, v7
	global_store_dword v[4:5], v2, off offset:128
.LBB0_891:
	s_or_b64 exec, exec, s[6:7]
	v_mul_f32_e32 v2, v8, v6
	s_nop 1
	v_mov_b32_dpp v6, v2 quad_perm:[1,0,3,2] row_mask:0xf bank_mask:0xf
	s_and_saveexec_b64 s[6:7], s[4:5]
	s_cbranch_execz .LBB0_893
	s_waitcnt lgkmcnt(0)
	v_cvt_pk_bf16_f32 v2, v2, v6
	global_store_dword v[4:5], v2, off offset:192
.LBB0_893:
	s_or_b64 exec, exec, s[6:7]
	s_waitcnt lgkmcnt(0)
	v_rcp_f32_e32 v6, v77
	v_or_b32_e32 v2, 9, v151
	v_or_b32_e32 v20, s28, v2
	v_lshlrev_b32_e32 v2, 12, v2
	v_mul_f32_e32 v7, v57, v6
	s_nop 1
	v_mov_b32_dpp v8, v7 quad_perm:[1,0,3,2] row_mask:0xf bank_mask:0xf
	v_cmp_gt_i32_e64 s[6:7], s23, v20
	v_lshl_add_u64 v[4:5], v[84:85], 0, v[2:3]
	s_and_b64 s[4:5], vcc, s[6:7]
	s_and_saveexec_b64 s[6:7], s[4:5]
	s_cbranch_execz .LBB0_895
	s_waitcnt lgkmcnt(0)
	v_cvt_pk_bf16_f32 v2, v7, v8
	global_store_dword v[4:5], v2, off
.LBB0_895:
	s_or_b64 exec, exec, s[6:7]
	v_mul_f32_e32 v2, v41, v6
	s_nop 1
	v_mov_b32_dpp v7, v2 quad_perm:[1,0,3,2] row_mask:0xf bank_mask:0xf
	s_and_saveexec_b64 s[6:7], s[4:5]
	s_cbranch_execz .LBB0_897
	s_waitcnt lgkmcnt(0)
	v_cvt_pk_bf16_f32 v2, v2, v7
	global_store_dword v[4:5], v2, off offset:64
.LBB0_897:
	s_or_b64 exec, exec, s[6:7]
	v_mul_f32_e32 v2, v25, v6
	s_waitcnt lgkmcnt(0)
	s_nop 1
	v_mov_b32_dpp v7, v2 quad_perm:[1,0,3,2] row_mask:0xf bank_mask:0xf
	s_and_saveexec_b64 s[6:7], s[4:5]
	s_cbranch_execz .LBB0_899
	s_waitcnt lgkmcnt(0)
	v_cvt_pk_bf16_f32 v2, v2, v7
	global_store_dword v[4:5], v2, off offset:128
.LBB0_899:
	s_or_b64 exec, exec, s[6:7]
	v_mul_f32_e32 v2, v9, v6
	s_nop 1
	v_mov_b32_dpp v6, v2 quad_perm:[1,0,3,2] row_mask:0xf bank_mask:0xf
	s_and_saveexec_b64 s[6:7], s[4:5]
	s_cbranch_execz .LBB0_901
	s_waitcnt lgkmcnt(0)
	v_cvt_pk_bf16_f32 v2, v2, v6
	global_store_dword v[4:5], v2, off offset:192
.LBB0_901:
	s_or_b64 exec, exec, s[6:7]
	s_waitcnt lgkmcnt(0)
	v_rcp_f32_e32 v6, v78
	v_or_b32_e32 v2, 10, v151
	v_or_b32_e32 v9, s28, v2
	v_lshlrev_b32_e32 v2, 12, v2
	v_mul_f32_e32 v7, v58, v6
	s_nop 1
	v_mov_b32_dpp v8, v7 quad_perm:[1,0,3,2] row_mask:0xf bank_mask:0xf
	v_cmp_gt_i32_e64 s[6:7], s23, v9
	v_lshl_add_u64 v[4:5], v[84:85], 0, v[2:3]
	s_and_b64 s[4:5], vcc, s[6:7]
	s_and_saveexec_b64 s[6:7], s[4:5]
	s_cbranch_execz .LBB0_903
	s_waitcnt lgkmcnt(0)
	v_cvt_pk_bf16_f32 v2, v7, v8
	global_store_dword v[4:5], v2, off
.LBB0_903:
	s_or_b64 exec, exec, s[6:7]
	v_mul_f32_e32 v2, v42, v6
	s_nop 1
	v_mov_b32_dpp v7, v2 quad_perm:[1,0,3,2] row_mask:0xf bank_mask:0xf
	s_and_saveexec_b64 s[6:7], s[4:5]
	s_cbranch_execz .LBB0_905
	s_waitcnt lgkmcnt(0)
	v_cvt_pk_bf16_f32 v2, v2, v7
	global_store_dword v[4:5], v2, off offset:64
.LBB0_905:
	s_or_b64 exec, exec, s[6:7]
	v_mul_f32_e32 v2, v26, v6
	s_waitcnt lgkmcnt(0)
	s_nop 1
	v_mov_b32_dpp v7, v2 quad_perm:[1,0,3,2] row_mask:0xf bank_mask:0xf
	s_and_saveexec_b64 s[6:7], s[4:5]
	s_cbranch_execz .LBB0_907
	s_waitcnt lgkmcnt(0)
	v_cvt_pk_bf16_f32 v2, v2, v7
	global_store_dword v[4:5], v2, off offset:128
; __device__ __forceinline__ unsigned cvt_pk_bf16(float lo, float hi) { unsigned r; asm volatile("v_cvt_pk_bf16_f32 %0, %1, %2" : "=v"(r) : "v"(lo), "v"(hi)); return r; }
; __device__ __forceinline__ int crow(int r, int hi) { return (r & 3) + 8 * (r >> 2) + 4 * hi; }
; template <int MODE, bool SAMPLE>
; __device__ __forceinline__ void unit(LAS char* lds, const UnitDesc& D) {
;     ...
;     if (wact) {
;         float rli[16];
;         if (MODE == 0) { if (hi == 0) ws[32 + r32] = l_reg; asm volatile("s_waitcnt lgkmcnt(0)" ::: "memory");
; #pragma unroll
;             for (int r = 0; r < 16; ++r) rli[r] = __builtin_amdgcn_rcpf(ws[32 + crow(r, hi)]); }
;         bf16* Ow = D.O + (size_t)(wid * 32) * DM;
; #pragma unroll
;         for (int r = 0; r < 16; ++r) { const int orow = crow(r, hi);
; #pragma unroll
;             for (int d0 = 0; d0 < 4; ++d0) { const float v = MODE == 0 ? o[d0][r] * rli[r] : o[d0][r];
;                 const float vn = __shfl_xor(v, 1);
;                 if ((r32 & 1) == 0 && wid * 32 + orow < D.nq) *(unsigned*)(Ow + (size_t)orow * DM + d0 * 32 + r32) = cvt_pk_bf16(v, vn); } }
.LBB0_907:
	s_or_b64 exec, exec, s[6:7]
	v_mul_f32_e32 v2, v10, v6
	s_nop 1
	v_mov_b32_dpp v6, v2 quad_perm:[1,0,3,2] row_mask:0xf bank_mask:0xf
	s_and_saveexec_b64 s[6:7], s[4:5]
	s_cbranch_execz .LBB0_909
	s_waitcnt lgkmcnt(0)
	v_cvt_pk_bf16_f32 v2, v2, v6
	global_store_dword v[4:5], v2, off offset:192
.LBB0_909:
	s_or_b64 exec, exec, s[6:7]
	s_waitcnt lgkmcnt(0)
	v_rcp_f32_e32 v6, v79
	v_or_b32_e32 v2, 11, v151
	v_or_b32_e32 v9, s28, v2
	v_lshlrev_b32_e32 v2, 12, v2
	v_mul_f32_e32 v7, v59, v6
	s_nop 1
	v_mov_b32_dpp v8, v7 quad_perm:[1,0,3,2] row_mask:0xf bank_mask:0xf
	v_cmp_gt_i32_e64 s[6:7], s23, v9
	v_lshl_add_u64 v[4:5], v[84:85], 0, v[2:3]
	s_and_b64 s[4:5], vcc, s[6:7]
	s_and_saveexec_b64 s[6:7], s[4:5]
	s_cbranch_execz .LBB0_911
	s_waitcnt lgkmcnt(0)
	v_cvt_pk_bf16_f32 v2, v7, v8
	global_store_dword v[4:5], v2, off
.LBB0_911:
	s_or_b64 exec, exec, s[6:7]
	v_mul_f32_e32 v2, v43, v6
	s_nop 1
	v_mov_b32_dpp v7, v2 quad_perm:[1,0,3,2] row_mask:0xf bank_mask:0xf
	s_and_saveexec_b64 s[6:7], s[4:5]
	s_cbranch_execz .LBB0_913
	s_waitcnt lgkmcnt(0)
	v_cvt_pk_bf16_f32 v2, v2, v7
	global_store_dword v[4:5], v2, off offset:64
.LBB0_913:
	s_or_b64 exec, exec, s[6:7]
	v_mul_f32_e32 v2, v27, v6
	s_waitcnt lgkmcnt(0)
	s_nop 1
	v_mov_b32_dpp v7, v2 quad_perm:[1,0,3,2] row_mask:0xf bank_mask:0xf
	s_and_saveexec_b64 s[6:7], s[4:5]
	s_cbranch_execz .LBB0_915
	s_waitcnt lgkmcnt(0)
	v_cvt_pk_bf16_f32 v2, v2, v7
	global_store_dword v[4:5], v2, off offset:128
.LBB0_915:
	s_or_b64 exec, exec, s[6:7]
	v_mul_f32_e32 v2, v11, v6
	s_nop 1
	v_mov_b32_dpp v6, v2 quad_perm:[1,0,3,2] row_mask:0xf bank_mask:0xf
	s_and_saveexec_b64 s[6:7], s[4:5]
	s_cbranch_execz .LBB0_917
	s_waitcnt lgkmcnt(0)
	v_cvt_pk_bf16_f32 v2, v2, v6
	global_store_dword v[4:5], v2, off offset:192
.LBB0_917:
	s_or_b64 exec, exec, s[6:7]
	s_waitcnt lgkmcnt(0)
	v_rcp_f32_e32 v6, v72
	v_or_b32_e32 v2, 16, v151
	v_or_b32_e32 v9, s28, v2
	v_lshlrev_b32_e32 v2, 12, v2
	v_mul_f32_e32 v7, v60, v6
	s_nop 1
	v_mov_b32_dpp v8, v7 quad_perm:[1,0,3,2] row_mask:0xf bank_mask:0xf
	v_cmp_gt_i32_e64 s[6:7], s23, v9
	v_lshl_add_u64 v[4:5], v[84:85], 0, v[2:3]
	s_and_b64 s[4:5], vcc, s[6:7]
	s_and_saveexec_b64 s[6:7], s[4:5]
	s_cbranch_execz .LBB0_919
	s_waitcnt lgkmcnt(0)
	v_cvt_pk_bf16_f32 v2, v7, v8
	global_store_dword v[4:5], v2, off
.LBB0_919:
	s_or_b64 exec, exec, s[6:7]
	v_mul_f32_e32 v2, v44, v6
	s_nop 1
	v_mov_b32_dpp v7, v2 quad_perm:[1,0,3,2] row_mask:0xf bank_mask:0xf
	s_and_saveexec_b64 s[6:7], s[4:5]
	s_cbranch_execz .LBB0_921
	s_waitcnt lgkmcnt(0)
	v_cvt_pk_bf16_f32 v2, v2, v7
	global_store_dword v[4:5], v2, off offset:64
.LBB0_921:
	s_or_b64 exec, exec, s[6:7]
	v_mul_f32_e32 v2, v28, v6
	s_waitcnt lgkmcnt(0)
	s_nop 1
	v_mov_b32_dpp v7, v2 quad_perm:[1,0,3,2] row_mask:0xf bank_mask:0xf
	s_and_saveexec_b64 s[6:7], s[4:5]
	s_cbranch_execz .LBB0_923
	s_waitcnt lgkmcnt(0)
	v_cvt_pk_bf16_f32 v2, v2, v7
	global_store_dword v[4:5], v2, off offset:128
.LBB0_923:
	s_or_b64 exec, exec, s[6:7]
	v_mul_f32_e32 v2, v12, v6
	s_nop 1
	v_mov_b32_dpp v6, v2 quad_perm:[1,0,3,2] row_mask:0xf bank_mask:0xf
	s_and_saveexec_b64 s[6:7], s[4:5]
	s_cbranch_execz .LBB0_925
	s_waitcnt lgkmcnt(0)
	v_cvt_pk_bf16_f32 v2, v2, v6
	global_store_dword v[4:5], v2, off offset:192
.LBB0_925:
	s_or_b64 exec, exec, s[6:7]
	s_waitcnt lgkmcnt(0)
	v_rcp_f32_e32 v6, v73
	v_or_b32_e32 v2, 17, v151
	v_or_b32_e32 v9, s28, v2
	v_lshlrev_b32_e32 v2, 12, v2
	v_mul_f32_e32 v7, v61, v6
	s_nop 1
	v_mov_b32_dpp v8, v7 quad_perm:[1,0,3,2] row_mask:0xf bank_mask:0xf
	v_cmp_gt_i32_e64 s[6:7], s23, v9
	v_lshl_add_u64 v[4:5], v[84:85], 0, v[2:3]
	s_and_b64 s[4:5], vcc, s[6:7]
	s_and_saveexec_b64 s[6:7], s[4:5]
	s_cbranch_execz .LBB0_927
	s_waitcnt lgkmcnt(0)
	v_cvt_pk_bf16_f32 v2, v7, v8
	global_store_dword v[4:5], v2, off
.LBB0_927:
	s_or_b64 exec, exec, s[6:7]
	v_mul_f32_e32 v2, v45, v6
	s_nop 1
	v_mov_b32_dpp v7, v2 quad_perm:[1,0,3,2] row_mask:0xf bank_mask:0xf
	s_and_saveexec_b64 s[6:7], s[4:5]
	s_cbranch_execz .LBB0_929
	s_waitcnt lgkmcnt(0)
	v_cvt_pk_bf16_f32 v2, v2, v7
	global_store_dword v[4:5], v2, off offset:64
.LBB0_929:
	s_or_b64 exec, exec, s[6:7]
	v_mul_f32_e32 v2, v29, v6
	s_waitcnt lgkmcnt(0)
	s_nop 1
	v_mov_b32_dpp v7, v2 quad_perm:[1,0,3,2] row_mask:0xf bank_mask:0xf
	s_and_saveexec_b64 s[6:7], s[4:5]
	s_cbranch_execz .LBB0_931
	s_waitcnt lgkmcnt(0)
	v_cvt_pk_bf16_f32 v2, v2, v7
	global_store_dword v[4:5], v2, off offset:128
.LBB0_931:
	s_or_b64 exec, exec, s[6:7]
	v_mul_f32_e32 v2, v13, v6
	s_nop 1
	v_mov_b32_dpp v6, v2 quad_perm:[1,0,3,2] row_mask:0xf bank_mask:0xf
	s_and_saveexec_b64 s[6:7], s[4:5]
	s_cbranch_execz .LBB0_933
	s_waitcnt lgkmcnt(0)
	v_cvt_pk_bf16_f32 v2, v2, v6
	global_store_dword v[4:5], v2, off offset:192
.LBB0_933:
	s_or_b64 exec, exec, s[6:7]
	s_waitcnt lgkmcnt(0)
	v_rcp_f32_e32 v6, v74
	v_or_b32_e32 v2, 18, v151
	v_or_b32_e32 v9, s28, v2
	v_lshlrev_b32_e32 v2, 12, v2
	v_mul_f32_e32 v7, v62, v6
	s_nop 1
	v_mov_b32_dpp v8, v7 quad_perm:[1,0,3,2] row_mask:0xf bank_mask:0xf
	v_cmp_gt_i32_e64 s[6:7], s23, v9
	v_lshl_add_u64 v[4:5], v[84:85], 0, v[2:3]
	s_and_b64 s[4:5], vcc, s[6:7]
	s_and_saveexec_b64 s[6:7], s[4:5]
	s_cbranch_execz .LBB0_935
	s_waitcnt lgkmcnt(0)
	v_cvt_pk_bf16_f32 v2, v7, v8
	global_store_dword v[4:5], v2, off
.LBB0_935:
	s_or_b64 exec, exec, s[6:7]
	v_mul_f32_e32 v2, v46, v6
	s_nop 1
	v_mov_b32_dpp v7, v2 quad_perm:[1,0,3,2] row_mask:0xf bank_mask:0xf
	s_and_saveexec_b64 s[6:7], s[4:5]
	s_cbranch_execz .LBB0_937
	s_waitcnt lgkmcnt(0)
	v_cvt_pk_bf16_f32 v2, v2, v7
	global_store_dword v[4:5], v2, off offset:64
; __device__ __forceinline__ unsigned cvt_pk_bf16(float lo, float hi) { unsigned r; asm volatile("v_cvt_pk_bf16_f32 %0, %1, %2" : "=v"(r) : "v"(lo), "v"(hi)); return r; }
; __device__ __forceinline__ int crow(int r, int hi) { return (r & 3) + 8 * (r >> 2) + 4 * hi; }
; template <int MODE, bool SAMPLE>
; __device__ __forceinline__ void unit(LAS char* lds, const UnitDesc& D) {
;     ...
;     if (wact) {
;         float rli[16];
;         if (MODE == 0) { if (hi == 0) ws[32 + r32] = l_reg; asm volatile("s_waitcnt lgkmcnt(0)" ::: "memory");
; #pragma unroll
;             for (int r = 0; r < 16; ++r) rli[r] = __builtin_amdgcn_rcpf(ws[32 + crow(r, hi)]); }
;         bf16* Ow = D.O + (size_t)(wid * 32) * DM;
; #pragma unroll
;         for (int r = 0; r < 16; ++r) { const int orow = crow(r, hi);
; #pragma unroll
;             for (int d0 = 0; d0 < 4; ++d0) { const float v = MODE == 0 ? o[d0][r] * rli[r] : o[d0][r];
;                 const float vn = __shfl_xor(v, 1);
;                 if ((r32 & 1) == 0 && wid * 32 + orow < D.nq) *(unsigned*)(Ow + (size_t)orow * DM + d0 * 32 + r32) = cvt_pk_bf16(v, vn); } }
.LBB0_937:
	s_or_b64 exec, exec, s[6:7]
	v_mul_f32_e32 v2, v30, v6
	s_waitcnt lgkmcnt(0)
	s_nop 1
	v_mov_b32_dpp v7, v2 quad_perm:[1,0,3,2] row_mask:0xf bank_mask:0xf
	s_and_saveexec_b64 s[6:7], s[4:5]
	s_cbranch_execz .LBB0_939
	s_waitcnt lgkmcnt(0)
	v_cvt_pk_bf16_f32 v2, v2, v7
	global_store_dword v[4:5], v2, off offset:128
.LBB0_939:
	s_or_b64 exec, exec, s[6:7]
	v_mul_f32_e32 v2, v14, v6
	s_nop 1
	v_mov_b32_dpp v6, v2 quad_perm:[1,0,3,2] row_mask:0xf bank_mask:0xf
	s_and_saveexec_b64 s[6:7], s[4:5]
	s_cbranch_execz .LBB0_941
	s_waitcnt lgkmcnt(0)
	v_cvt_pk_bf16_f32 v2, v2, v6
	global_store_dword v[4:5], v2, off offset:192
.LBB0_941:
	s_or_b64 exec, exec, s[6:7]
	s_waitcnt lgkmcnt(0)
	v_rcp_f32_e32 v6, v75
	v_or_b32_e32 v2, 19, v151
	v_or_b32_e32 v9, s28, v2
	v_lshlrev_b32_e32 v2, 12, v2
	v_mul_f32_e32 v7, v63, v6
	s_nop 1
	v_mov_b32_dpp v8, v7 quad_perm:[1,0,3,2] row_mask:0xf bank_mask:0xf
	v_cmp_gt_i32_e64 s[6:7], s23, v9
	v_lshl_add_u64 v[4:5], v[84:85], 0, v[2:3]
	s_and_b64 s[4:5], vcc, s[6:7]
	s_and_saveexec_b64 s[6:7], s[4:5]
	s_cbranch_execz .LBB0_943
	s_waitcnt lgkmcnt(0)
	v_cvt_pk_bf16_f32 v2, v7, v8
	global_store_dword v[4:5], v2, off
.LBB0_943:
	s_or_b64 exec, exec, s[6:7]
	v_mul_f32_e32 v2, v47, v6
	s_nop 1
	v_mov_b32_dpp v7, v2 quad_perm:[1,0,3,2] row_mask:0xf bank_mask:0xf
	s_and_saveexec_b64 s[6:7], s[4:5]
	s_cbranch_execz .LBB0_945
	s_waitcnt lgkmcnt(0)
	v_cvt_pk_bf16_f32 v2, v2, v7
	global_store_dword v[4:5], v2, off offset:64
.LBB0_945:
	s_or_b64 exec, exec, s[6:7]
	v_mul_f32_e32 v2, v31, v6
	s_waitcnt lgkmcnt(0)
	s_nop 1
	v_mov_b32_dpp v7, v2 quad_perm:[1,0,3,2] row_mask:0xf bank_mask:0xf
	s_and_saveexec_b64 s[6:7], s[4:5]
	s_cbranch_execz .LBB0_947
	s_waitcnt lgkmcnt(0)
	v_cvt_pk_bf16_f32 v2, v2, v7
	global_store_dword v[4:5], v2, off offset:128
.LBB0_947:
	s_or_b64 exec, exec, s[6:7]
	v_mul_f32_e32 v2, v15, v6
	s_nop 1
	v_mov_b32_dpp v6, v2 quad_perm:[1,0,3,2] row_mask:0xf bank_mask:0xf
	s_and_saveexec_b64 s[6:7], s[4:5]
	s_cbranch_execz .LBB0_949
	s_waitcnt lgkmcnt(0)
	v_cvt_pk_bf16_f32 v2, v2, v6
	global_store_dword v[4:5], v2, off offset:192
.LBB0_949:
	s_or_b64 exec, exec, s[6:7]
	s_waitcnt lgkmcnt(0)
	v_rcp_f32_e32 v6, v68
	v_or_b32_e32 v2, 24, v151
	v_or_b32_e32 v9, s28, v2
	v_lshlrev_b32_e32 v2, 12, v2
	v_mul_f32_e32 v7, v64, v6
	s_nop 1
	v_mov_b32_dpp v8, v7 quad_perm:[1,0,3,2] row_mask:0xf bank_mask:0xf
	v_cmp_gt_i32_e64 s[6:7], s23, v9
	v_lshl_add_u64 v[4:5], v[84:85], 0, v[2:3]
	s_and_b64 s[4:5], vcc, s[6:7]
	s_and_saveexec_b64 s[6:7], s[4:5]
	s_cbranch_execz .LBB0_951
	s_waitcnt lgkmcnt(0)
	v_cvt_pk_bf16_f32 v2, v7, v8
	global_store_dword v[4:5], v2, off
.LBB0_951:
	s_or_b64 exec, exec, s[6:7]
	v_mul_f32_e32 v2, v48, v6
	s_nop 1
	v_mov_b32_dpp v7, v2 quad_perm:[1,0,3,2] row_mask:0xf bank_mask:0xf
	s_and_saveexec_b64 s[6:7], s[4:5]
	s_cbranch_execz .LBB0_953
	s_waitcnt lgkmcnt(0)
	v_cvt_pk_bf16_f32 v2, v2, v7
	global_store_dword v[4:5], v2, off offset:64
.LBB0_953:
	s_or_b64 exec, exec, s[6:7]
	v_mul_f32_e32 v2, v32, v6
	s_waitcnt lgkmcnt(0)
	s_nop 1
	v_mov_b32_dpp v7, v2 quad_perm:[1,0,3,2] row_mask:0xf bank_mask:0xf
	s_and_saveexec_b64 s[6:7], s[4:5]
	s_cbranch_execz .LBB0_955
	s_waitcnt lgkmcnt(0)
	v_cvt_pk_bf16_f32 v2, v2, v7
	global_store_dword v[4:5], v2, off offset:128
.LBB0_955:
	s_or_b64 exec, exec, s[6:7]
	v_mul_f32_e32 v2, v16, v6
	s_nop 1
	v_mov_b32_dpp v6, v2 quad_perm:[1,0,3,2] row_mask:0xf bank_mask:0xf
	s_and_saveexec_b64 s[6:7], s[4:5]
	s_cbranch_execz .LBB0_957
	s_waitcnt lgkmcnt(0)
	v_cvt_pk_bf16_f32 v2, v2, v6
	global_store_dword v[4:5], v2, off offset:192
.LBB0_957:
	s_or_b64 exec, exec, s[6:7]
	s_waitcnt lgkmcnt(0)
	v_rcp_f32_e32 v6, v69
	v_or_b32_e32 v2, 25, v151
	v_or_b32_e32 v9, s28, v2
	v_lshlrev_b32_e32 v2, 12, v2
	v_mul_f32_e32 v7, v65, v6
	s_nop 1
	v_mov_b32_dpp v8, v7 quad_perm:[1,0,3,2] row_mask:0xf bank_mask:0xf
	v_cmp_gt_i32_e64 s[6:7], s23, v9
	v_lshl_add_u64 v[4:5], v[84:85], 0, v[2:3]
	s_and_b64 s[4:5], vcc, s[6:7]
	s_and_saveexec_b64 s[6:7], s[4:5]
	s_cbranch_execz .LBB0_959
	s_waitcnt lgkmcnt(0)
	v_cvt_pk_bf16_f32 v2, v7, v8
	global_store_dword v[4:5], v2, off
; __device__ __forceinline__ unsigned cvt_pk_bf16(float lo, float hi) { unsigned r; asm volatile("v_cvt_pk_bf16_f32 %0, %1, %2" : "=v"(r) : "v"(lo), "v"(hi)); return r; }
; __device__ __forceinline__ int crow(int r, int hi) { return (r & 3) + 8 * (r >> 2) + 4 * hi; }
; template <int MODE, bool SAMPLE>
; __device__ __forceinline__ void unit(LAS char* lds, const UnitDesc& D) {
;     ...
;     if (wact) {
;         float rli[16];
;         if (MODE == 0) { if (hi == 0) ws[32 + r32] = l_reg; asm volatile("s_waitcnt lgkmcnt(0)" ::: "memory");
; #pragma unroll
;             for (int r = 0; r < 16; ++r) rli[r] = __builtin_amdgcn_rcpf(ws[32 + crow(r, hi)]); }
;         bf16* Ow = D.O + (size_t)(wid * 32) * DM;
; #pragma unroll
;         for (int r = 0; r < 16; ++r) { const int orow = crow(r, hi);
; #pragma unroll
;             for (int d0 = 0; d0 < 4; ++d0) { const float v = MODE == 0 ? o[d0][r] * rli[r] : o[d0][r];
;                 const float vn = __shfl_xor(v, 1);
;                 if ((r32 & 1) == 0 && wid * 32 + orow < D.nq) *(unsigned*)(Ow + (size_t)orow * DM + d0 * 32 + r32) = cvt_pk_bf16(v, vn); } }
.LBB0_959:
	s_or_b64 exec, exec, s[6:7]
	v_mul_f32_e32 v2, v49, v6
	s_nop 1
	v_mov_b32_dpp v7, v2 quad_perm:[1,0,3,2] row_mask:0xf bank_mask:0xf
	s_and_saveexec_b64 s[6:7], s[4:5]
	s_cbranch_execz .LBB0_961
	s_waitcnt lgkmcnt(0)
	v_cvt_pk_bf16_f32 v2, v2, v7
	global_store_dword v[4:5], v2, off offset:64
.LBB0_961:
	s_or_b64 exec, exec, s[6:7]
	v_mul_f32_e32 v2, v33, v6
	s_waitcnt lgkmcnt(0)
	s_nop 1
	v_mov_b32_dpp v7, v2 quad_perm:[1,0,3,2] row_mask:0xf bank_mask:0xf
	s_and_saveexec_b64 s[6:7], s[4:5]
	s_cbranch_execz .LBB0_963
	s_waitcnt lgkmcnt(0)
	v_cvt_pk_bf16_f32 v2, v2, v7
	global_store_dword v[4:5], v2, off offset:128
.LBB0_963:
	s_or_b64 exec, exec, s[6:7]
	v_mul_f32_e32 v2, v17, v6
	s_nop 1
	v_mov_b32_dpp v6, v2 quad_perm:[1,0,3,2] row_mask:0xf bank_mask:0xf
	s_and_saveexec_b64 s[6:7], s[4:5]
	s_cbranch_execz .LBB0_965
	s_waitcnt lgkmcnt(0)
	v_cvt_pk_bf16_f32 v2, v2, v6
	global_store_dword v[4:5], v2, off offset:192
.LBB0_965:
	s_or_b64 exec, exec, s[6:7]
	s_waitcnt lgkmcnt(0)
	v_rcp_f32_e32 v6, v70
	v_or_b32_e32 v2, 26, v151
	v_or_b32_e32 v9, s28, v2
	v_lshlrev_b32_e32 v2, 12, v2
	v_mul_f32_e32 v7, v66, v6
	s_nop 1
	v_mov_b32_dpp v8, v7 quad_perm:[1,0,3,2] row_mask:0xf bank_mask:0xf
	v_cmp_gt_i32_e64 s[6:7], s23, v9
	v_lshl_add_u64 v[4:5], v[84:85], 0, v[2:3]
	s_and_b64 s[4:5], vcc, s[6:7]
	s_and_saveexec_b64 s[6:7], s[4:5]
	s_cbranch_execz .LBB0_967
	s_waitcnt lgkmcnt(0)
	v_cvt_pk_bf16_f32 v2, v7, v8
	global_store_dword v[4:5], v2, off
.LBB0_967:
	s_or_b64 exec, exec, s[6:7]
	v_mul_f32_e32 v2, v50, v6
	s_nop 1
	v_mov_b32_dpp v7, v2 quad_perm:[1,0,3,2] row_mask:0xf bank_mask:0xf
	s_and_saveexec_b64 s[6:7], s[4:5]
	s_cbranch_execz .LBB0_969
	s_waitcnt lgkmcnt(0)
	v_cvt_pk_bf16_f32 v2, v2, v7
	global_store_dword v[4:5], v2, off offset:64
.LBB0_969:
	s_or_b64 exec, exec, s[6:7]
	v_mul_f32_e32 v2, v34, v6
	s_waitcnt lgkmcnt(0)
	s_nop 1
	v_mov_b32_dpp v7, v2 quad_perm:[1,0,3,2] row_mask:0xf bank_mask:0xf
	s_and_saveexec_b64 s[6:7], s[4:5]
	s_cbranch_execz .LBB0_971
	s_waitcnt lgkmcnt(0)
	v_cvt_pk_bf16_f32 v2, v2, v7
	global_store_dword v[4:5], v2, off offset:128
.LBB0_971:
	s_or_b64 exec, exec, s[6:7]
	v_mul_f32_e32 v2, v18, v6
	s_nop 1
	v_mov_b32_dpp v6, v2 quad_perm:[1,0,3,2] row_mask:0xf bank_mask:0xf
	s_and_saveexec_b64 s[6:7], s[4:5]
	s_cbranch_execz .LBB0_973
	s_waitcnt lgkmcnt(0)
	v_cvt_pk_bf16_f32 v2, v2, v6
	global_store_dword v[4:5], v2, off offset:192
.LBB0_973:
	s_or_b64 exec, exec, s[6:7]
	s_waitcnt lgkmcnt(0)
	v_rcp_f32_e32 v6, v71
	v_or_b32_e32 v2, 27, v151
	v_or_b32_e32 v9, s28, v2
	v_lshlrev_b32_e32 v2, 12, v2
	v_mul_f32_e32 v7, v67, v6
	s_nop 1
	v_mov_b32_dpp v8, v7 quad_perm:[1,0,3,2] row_mask:0xf bank_mask:0xf
	v_cmp_gt_i32_e64 s[6:7], s23, v9
	v_lshl_add_u64 v[4:5], v[84:85], 0, v[2:3]
	s_and_b64 s[4:5], vcc, s[6:7]
	s_and_saveexec_b64 s[6:7], s[4:5]
	s_cbranch_execz .LBB0_975
	s_waitcnt lgkmcnt(0)
	v_cvt_pk_bf16_f32 v2, v7, v8
	global_store_dword v[4:5], v2, off
.LBB0_975:
	s_or_b64 exec, exec, s[6:7]
	v_mul_f32_e32 v2, v51, v6
	s_nop 1
	v_mov_b32_dpp v7, v2 quad_perm:[1,0,3,2] row_mask:0xf bank_mask:0xf
	s_and_saveexec_b64 s[6:7], s[4:5]
	s_cbranch_execz .LBB0_977
	s_waitcnt lgkmcnt(0)
	v_cvt_pk_bf16_f32 v2, v2, v7
	global_store_dword v[4:5], v2, off offset:64
.LBB0_977:
	s_or_b64 exec, exec, s[6:7]
	v_mul_f32_e32 v2, v35, v6
	s_waitcnt lgkmcnt(0)
	s_nop 1
	v_mov_b32_dpp v7, v2 quad_perm:[1,0,3,2] row_mask:0xf bank_mask:0xf
	s_and_saveexec_b64 s[6:7], s[4:5]
	s_cbranch_execz .LBB0_979
	s_waitcnt lgkmcnt(0)
	v_cvt_pk_bf16_f32 v2, v2, v7
	global_store_dword v[4:5], v2, off offset:128
.LBB0_979:
	s_or_b64 exec, exec, s[6:7]
	v_mul_f32_e32 v2, v19, v6
	s_nop 1
	v_mov_b32_dpp v6, v2 quad_perm:[1,0,3,2] row_mask:0xf bank_mask:0xf
	s_and_saveexec_b64 s[6:7], s[4:5]
	s_cbranch_execz .LBB0_817
	s_waitcnt lgkmcnt(0)
	v_cvt_pk_bf16_f32 v2, v2, v6
	global_store_dword v[4:5], v2, off offset:192
	s_branch .LBB0_817

; __device__ __forceinline__ unsigned cvt_pk_bf16(float lo, float hi) { unsigned r; asm volatile("v_cvt_pk_bf16_f32 %0, %1, %2" : "=v"(r) : "v"(lo), "v"(hi)); return r; }
; __device__ __forceinline__ int crow(int r, int hi) { return (r & 3) + 8 * (r >> 2) + 4 * hi; }
; template <int MODE, bool SAMPLE>
; __device__ __forceinline__ void unit(LAS char* lds, const UnitDesc& D) {
;     ...
;         bf16* Ow = D.O + (size_t)(wid * 32) * DM;
; #pragma unroll
;         for (int r = 0; r < 16; ++r) { const int orow = crow(r, hi);
; #pragma unroll
;             for (int d0 = 0; d0 < 4; ++d0) { const float v = MODE == 0 ? o[d0][r] * rli[r] : o[d0][r];
;                 const float vn = __shfl_xor(v, 1);
;                 if ((r32 & 1) == 0 && wid * 32 + orow < D.nq) *(unsigned*)(Ow + (size_t)orow * DM + d0 * 32 + r32) = cvt_pk_bf16(v, vn); } }
.LBB0_1635:
	s_andn2_b64 vcc, exec, s[82:83]
	s_cbranch_vccnz .LBB0_1765
	v_readlane_b32 s2, v242, 10
	v_readlane_b32 s3, v242, 11
	s_add_u32 s2, s2, s4
	v_and_b32_e32 v67, 64, v202
	s_addc_u32 s3, s3, s5
	v_xor_b32_e32 v66, 1, v202
	v_add_u32_e32 v67, 64, v67
	s_add_u32 s4, s2, s9
	v_cmp_lt_i32_e32 vcc, v66, v67
	s_addc_u32 s5, s3, 0
	s_ashr_i32 s9, s8, 31
	v_cndmask_b32_e32 v66, v202, v66, vcc
	s_lshl_b64 s[2:3], s[8:9], 12
	v_lshlrev_b32_e32 v70, 2, v66
	s_add_u32 s2, s4, s2
	s_nop 1
	v_mov_b32_dpp v71, v50 quad_perm:[1,0,3,2] row_mask:0xf bank_mask:0xf
	s_addc_u32 s3, s5, s3
	v_and_b32_e32 v66, 1, v204
	v_lshlrev_b32_e32 v162, 1, v205
	v_cmp_eq_u32_e32 vcc, 0, v66
	v_lshl_add_u64 v[66:67], s[2:3], 0, v[162:163]
	s_mov_b64 s[2:3], 0x17500000
	v_or_b32_e32 v72, s8, v179
	v_lshl_add_u64 v[66:67], v[66:67], 0, s[2:3]
	v_lshlrev_b32_e32 v162, 14, v203
	v_cmp_gt_i32_e64 s[10:11], 16, v72
	v_lshl_add_u64 v[68:69], v[66:67], 0, v[162:163]
	s_and_b64 s[4:5], vcc, s[10:11]
	s_and_saveexec_b64 s[10:11], s[4:5]
	s_cbranch_execz .LBB0_1638
	s_waitcnt lgkmcnt(0)
	v_cvt_pk_bf16_f32 v50, v50, v71
	global_store_dword v[68:69], v50, off
.LBB0_1638:
	s_or_b64 exec, exec, s[10:11]
	s_nop 1
	v_mov_b32_dpp v50, v34 quad_perm:[1,0,3,2] row_mask:0xf bank_mask:0xf
	s_and_saveexec_b64 s[10:11], s[4:5]
	s_cbranch_execz .LBB0_1640
	s_waitcnt lgkmcnt(0)
	v_cvt_pk_bf16_f32 v34, v34, v50
	global_store_dword v[68:69], v34, off offset:64
.LBB0_1640:
	s_or_b64 exec, exec, s[10:11]
	s_nop 1
	v_mov_b32_dpp v34, v18 quad_perm:[1,0,3,2] row_mask:0xf bank_mask:0xf
	s_and_saveexec_b64 s[10:11], s[4:5]
	s_cbranch_execz .LBB0_1642
	s_waitcnt lgkmcnt(0)
	v_cvt_pk_bf16_f32 v18, v18, v34
	global_store_dword v[68:69], v18, off offset:128
.LBB0_1642:
	s_or_b64 exec, exec, s[10:11]
	s_nop 1
	v_mov_b32_dpp v18, v2 quad_perm:[1,0,3,2] row_mask:0xf bank_mask:0xf
	s_and_saveexec_b64 s[10:11], s[4:5]
	s_cbranch_execz .LBB0_1644
	s_waitcnt lgkmcnt(0)
	v_cvt_pk_bf16_f32 v2, v2, v18
	global_store_dword v[68:69], v2, off offset:192
.LBB0_1644:
	s_or_b64 exec, exec, s[10:11]
	s_nop 1
	v_mov_b32_dpp v2, v51 quad_perm:[1,0,3,2] row_mask:0xf bank_mask:0xf
	s_waitcnt lgkmcnt(0)
	v_or_b32_e32 v18, 1, v179
	v_or_b32_e32 v34, s8, v18
	v_lshlrev_b32_e32 v162, 12, v18
	v_cmp_gt_i32_e64 s[10:11], 16, v34
	v_lshl_add_u64 v[68:69], v[66:67], 0, v[162:163]
	s_and_b64 s[4:5], vcc, s[10:11]
	s_and_saveexec_b64 s[10:11], s[4:5]
	s_cbranch_execz .LBB0_1646
	s_waitcnt lgkmcnt(0)
	v_cvt_pk_bf16_f32 v2, v51, v2
	global_store_dword v[68:69], v2, off
.LBB0_1646:
	s_or_b64 exec, exec, s[10:11]
	s_waitcnt lgkmcnt(0)
	s_nop 1
	v_mov_b32_dpp v2, v35 quad_perm:[1,0,3,2] row_mask:0xf bank_mask:0xf
	s_and_saveexec_b64 s[10:11], s[4:5]
	s_cbranch_execz .LBB0_1648
	s_waitcnt lgkmcnt(0)
	v_cvt_pk_bf16_f32 v2, v35, v2
	global_store_dword v[68:69], v2, off offset:64
.LBB0_1648:
	s_or_b64 exec, exec, s[10:11]
	s_waitcnt lgkmcnt(0)
	s_nop 1
	v_mov_b32_dpp v2, v19 quad_perm:[1,0,3,2] row_mask:0xf bank_mask:0xf
	s_and_saveexec_b64 s[10:11], s[4:5]
	s_cbranch_execz .LBB0_1650
	s_waitcnt lgkmcnt(0)
	v_cvt_pk_bf16_f32 v2, v19, v2
	global_store_dword v[68:69], v2, off offset:128
.LBB0_1650:
	s_or_b64 exec, exec, s[10:11]
	s_waitcnt lgkmcnt(0)
	s_nop 1
	v_mov_b32_dpp v2, v3 quad_perm:[1,0,3,2] row_mask:0xf bank_mask:0xf
	s_and_saveexec_b64 s[10:11], s[4:5]
	s_cbranch_execz .LBB0_1652
	s_waitcnt lgkmcnt(0)
	v_cvt_pk_bf16_f32 v2, v3, v2
	global_store_dword v[68:69], v2, off offset:192
.LBB0_1652:
	s_or_b64 exec, exec, s[10:11]
	s_nop 1
	v_mov_b32_dpp v18, v52 quad_perm:[1,0,3,2] row_mask:0xf bank_mask:0xf
	s_waitcnt lgkmcnt(0)
	v_or_b32_e32 v2, 2, v179
	v_or_b32_e32 v19, s8, v2
	v_lshlrev_b32_e32 v162, 12, v2
	v_cmp_gt_i32_e64 s[10:11], 16, v19
	v_lshl_add_u64 v[2:3], v[66:67], 0, v[162:163]
	s_and_b64 s[4:5], vcc, s[10:11]
	s_and_saveexec_b64 s[10:11], s[4:5]
	s_cbranch_execz .LBB0_1654
	s_waitcnt lgkmcnt(0)
	v_cvt_pk_bf16_f32 v18, v52, v18
	global_store_dword v[2:3], v18, off
.LBB0_1654:
	s_or_b64 exec, exec, s[10:11]
	s_waitcnt lgkmcnt(0)
	s_nop 1
	v_mov_b32_dpp v18, v36 quad_perm:[1,0,3,2] row_mask:0xf bank_mask:0xf
	s_and_saveexec_b64 s[10:11], s[4:5]
	s_cbranch_execz .LBB0_1656
	s_waitcnt lgkmcnt(0)
	v_cvt_pk_bf16_f32 v18, v36, v18
	global_store_dword v[2:3], v18, off offset:64
.LBB0_1656:
	s_or_b64 exec, exec, s[10:11]
	s_waitcnt lgkmcnt(0)
	s_nop 1
	v_mov_b32_dpp v18, v20 quad_perm:[1,0,3,2] row_mask:0xf bank_mask:0xf
	s_and_saveexec_b64 s[10:11], s[4:5]
	s_cbranch_execz .LBB0_1658
	s_waitcnt lgkmcnt(0)
	v_cvt_pk_bf16_f32 v18, v20, v18
	global_store_dword v[2:3], v18, off offset:128
.LBB0_1658:
	s_or_b64 exec, exec, s[10:11]
	s_waitcnt lgkmcnt(0)
	s_nop 1
	v_mov_b32_dpp v18, v4 quad_perm:[1,0,3,2] row_mask:0xf bank_mask:0xf
	s_and_saveexec_b64 s[10:11], s[4:5]
	s_cbranch_execz .LBB0_1660
	s_waitcnt lgkmcnt(0)
	v_cvt_pk_bf16_f32 v4, v4, v18
	global_store_dword v[2:3], v4, off offset:192
.LBB0_1660:
	s_or_b64 exec, exec, s[10:11]
	s_nop 1
	v_mov_b32_dpp v4, v53 quad_perm:[1,0,3,2] row_mask:0xf bank_mask:0xf
	v_or_b32_e32 v2, 3, v179
	s_waitcnt lgkmcnt(0)
	v_or_b32_e32 v18, s8, v2
	v_lshlrev_b32_e32 v162, 12, v2
	v_cmp_gt_i32_e64 s[10:11], 16, v18
	v_lshl_add_u64 v[2:3], v[66:67], 0, v[162:163]
	s_and_b64 s[4:5], vcc, s[10:11]
	s_and_saveexec_b64 s[10:11], s[4:5]
	s_cbranch_execz .LBB0_1662
	s_waitcnt lgkmcnt(0)
	v_cvt_pk_bf16_f32 v4, v53, v4
	global_store_dword v[2:3], v4, off
.LBB0_1662:
	s_or_b64 exec, exec, s[10:11]
	s_waitcnt lgkmcnt(0)
	s_nop 1
	v_mov_b32_dpp v4, v37 quad_perm:[1,0,3,2] row_mask:0xf bank_mask:0xf
	s_and_saveexec_b64 s[10:11], s[4:5]
	s_cbranch_execz .LBB0_1664
	s_waitcnt lgkmcnt(0)
	v_cvt_pk_bf16_f32 v4, v37, v4
	global_store_dword v[2:3], v4, off offset:64
; __device__ __forceinline__ unsigned cvt_pk_bf16(float lo, float hi) { unsigned r; asm volatile("v_cvt_pk_bf16_f32 %0, %1, %2" : "=v"(r) : "v"(lo), "v"(hi)); return r; }
; __device__ __forceinline__ int crow(int r, int hi) { return (r & 3) + 8 * (r >> 2) + 4 * hi; }
; template <int MODE, bool SAMPLE>
; __device__ __forceinline__ void unit(LAS char* lds, const UnitDesc& D) {
;     ...
;         bf16* Ow = D.O + (size_t)(wid * 32) * DM;
; #pragma unroll
;         for (int r = 0; r < 16; ++r) { const int orow = crow(r, hi);
; #pragma unroll
;             for (int d0 = 0; d0 < 4; ++d0) { const float v = MODE == 0 ? o[d0][r] * rli[r] : o[d0][r];
;                 const float vn = __shfl_xor(v, 1);
;                 if ((r32 & 1) == 0 && wid * 32 + orow < D.nq) *(unsigned*)(Ow + (size_t)orow * DM + d0 * 32 + r32) = cvt_pk_bf16(v, vn); } }
.LBB0_1664:
	s_or_b64 exec, exec, s[10:11]
	s_waitcnt lgkmcnt(0)
	s_nop 1
	v_mov_b32_dpp v4, v21 quad_perm:[1,0,3,2] row_mask:0xf bank_mask:0xf
	s_and_saveexec_b64 s[10:11], s[4:5]
	s_cbranch_execz .LBB0_1666
	s_waitcnt lgkmcnt(0)
	v_cvt_pk_bf16_f32 v4, v21, v4
	global_store_dword v[2:3], v4, off offset:128
.LBB0_1666:
	s_or_b64 exec, exec, s[10:11]
	s_waitcnt lgkmcnt(0)
	s_nop 1
	v_mov_b32_dpp v4, v5 quad_perm:[1,0,3,2] row_mask:0xf bank_mask:0xf
	s_and_saveexec_b64 s[10:11], s[4:5]
	s_cbranch_execz .LBB0_1668
	s_waitcnt lgkmcnt(0)
	v_cvt_pk_bf16_f32 v4, v5, v4
	global_store_dword v[2:3], v4, off offset:192
.LBB0_1668:
	s_or_b64 exec, exec, s[10:11]
	s_waitcnt lgkmcnt(0)
	s_nop 1
	v_mov_b32_dpp v4, v54 quad_perm:[1,0,3,2] row_mask:0xf bank_mask:0xf
	v_or_b32_e32 v2, 8, v179
	v_or_b32_e32 v5, s8, v2
	v_lshlrev_b32_e32 v162, 12, v2
	v_cmp_gt_i32_e64 s[10:11], 16, v5
	v_lshl_add_u64 v[2:3], v[66:67], 0, v[162:163]
	s_and_b64 s[4:5], vcc, s[10:11]
	s_and_saveexec_b64 s[10:11], s[4:5]
	s_cbranch_execz .LBB0_1670
	s_waitcnt lgkmcnt(0)
	v_cvt_pk_bf16_f32 v4, v54, v4
	global_store_dword v[2:3], v4, off
.LBB0_1670:
	s_or_b64 exec, exec, s[10:11]
	s_waitcnt lgkmcnt(0)
	s_nop 1
	v_mov_b32_dpp v4, v38 quad_perm:[1,0,3,2] row_mask:0xf bank_mask:0xf
	s_and_saveexec_b64 s[10:11], s[4:5]
	s_cbranch_execz .LBB0_1672
	s_waitcnt lgkmcnt(0)
	v_cvt_pk_bf16_f32 v4, v38, v4
	global_store_dword v[2:3], v4, off offset:64
.LBB0_1672:
	s_or_b64 exec, exec, s[10:11]
	s_waitcnt lgkmcnt(0)
	s_nop 1
	v_mov_b32_dpp v4, v22 quad_perm:[1,0,3,2] row_mask:0xf bank_mask:0xf
	s_and_saveexec_b64 s[10:11], s[4:5]
	s_cbranch_execz .LBB0_1674
	s_waitcnt lgkmcnt(0)
	v_cvt_pk_bf16_f32 v4, v22, v4
	global_store_dword v[2:3], v4, off offset:128
.LBB0_1674:
	s_or_b64 exec, exec, s[10:11]
	s_waitcnt lgkmcnt(0)
	s_nop 1
	v_mov_b32_dpp v4, v6 quad_perm:[1,0,3,2] row_mask:0xf bank_mask:0xf
	s_and_saveexec_b64 s[10:11], s[4:5]
	s_cbranch_execz .LBB0_1676
	s_waitcnt lgkmcnt(0)
	v_cvt_pk_bf16_f32 v4, v6, v4
	global_store_dword v[2:3], v4, off offset:192
.LBB0_1676:
	s_or_b64 exec, exec, s[10:11]
	s_waitcnt lgkmcnt(0)
	s_nop 1
	v_mov_b32_dpp v4, v55 quad_perm:[1,0,3,2] row_mask:0xf bank_mask:0xf
	v_or_b32_e32 v2, 9, v179
	v_or_b32_e32 v5, s8, v2
	v_lshlrev_b32_e32 v162, 12, v2
	v_cmp_gt_i32_e64 s[10:11], 16, v5
	v_lshl_add_u64 v[2:3], v[66:67], 0, v[162:163]
	s_and_b64 s[4:5], vcc, s[10:11]
	s_and_saveexec_b64 s[10:11], s[4:5]
	s_cbranch_execz .LBB0_1678
	s_waitcnt lgkmcnt(0)
	v_cvt_pk_bf16_f32 v4, v55, v4
	global_store_dword v[2:3], v4, off
.LBB0_1678:
	s_or_b64 exec, exec, s[10:11]
	s_waitcnt lgkmcnt(0)
	s_nop 1
	v_mov_b32_dpp v4, v39 quad_perm:[1,0,3,2] row_mask:0xf bank_mask:0xf
	s_and_saveexec_b64 s[10:11], s[4:5]
	s_cbranch_execz .LBB0_1680
	s_waitcnt lgkmcnt(0)
	v_cvt_pk_bf16_f32 v4, v39, v4
	global_store_dword v[2:3], v4, off offset:64
.LBB0_1680:
	s_or_b64 exec, exec, s[10:11]
	s_waitcnt lgkmcnt(0)
	s_nop 1
	v_mov_b32_dpp v4, v23 quad_perm:[1,0,3,2] row_mask:0xf bank_mask:0xf
	s_and_saveexec_b64 s[10:11], s[4:5]
	s_cbranch_execz .LBB0_1682
	s_waitcnt lgkmcnt(0)
	v_cvt_pk_bf16_f32 v4, v23, v4
	global_store_dword v[2:3], v4, off offset:128
.LBB0_1682:
	s_or_b64 exec, exec, s[10:11]
	s_waitcnt lgkmcnt(0)
	s_nop 1
	v_mov_b32_dpp v4, v7 quad_perm:[1,0,3,2] row_mask:0xf bank_mask:0xf
	s_and_saveexec_b64 s[10:11], s[4:5]
	s_cbranch_execz .LBB0_1684
	s_waitcnt lgkmcnt(0)
	v_cvt_pk_bf16_f32 v4, v7, v4
	global_store_dword v[2:3], v4, off offset:192
.LBB0_1684:
	s_or_b64 exec, exec, s[10:11]
	s_waitcnt lgkmcnt(0)
	s_nop 1
	v_mov_b32_dpp v4, v56 quad_perm:[1,0,3,2] row_mask:0xf bank_mask:0xf
	v_or_b32_e32 v2, 10, v179
	v_or_b32_e32 v5, s8, v2
	v_lshlrev_b32_e32 v162, 12, v2
	v_cmp_gt_i32_e64 s[10:11], 16, v5
	v_lshl_add_u64 v[2:3], v[66:67], 0, v[162:163]
	s_and_b64 s[4:5], vcc, s[10:11]
	s_and_saveexec_b64 s[10:11], s[4:5]
	s_cbranch_execz .LBB0_1686
	s_waitcnt lgkmcnt(0)
	v_cvt_pk_bf16_f32 v4, v56, v4
	global_store_dword v[2:3], v4, off
.LBB0_1686:
	s_or_b64 exec, exec, s[10:11]
	s_waitcnt lgkmcnt(0)
	s_nop 1
	v_mov_b32_dpp v4, v40 quad_perm:[1,0,3,2] row_mask:0xf bank_mask:0xf
	s_and_saveexec_b64 s[10:11], s[4:5]
	s_cbranch_execz .LBB0_1688
	s_waitcnt lgkmcnt(0)
	v_cvt_pk_bf16_f32 v4, v40, v4
	global_store_dword v[2:3], v4, off offset:64
.LBB0_1688:
	s_or_b64 exec, exec, s[10:11]
	s_waitcnt lgkmcnt(0)
	s_nop 1
	v_mov_b32_dpp v4, v24 quad_perm:[1,0,3,2] row_mask:0xf bank_mask:0xf
	s_and_saveexec_b64 s[10:11], s[4:5]
	s_cbranch_execz .LBB0_1690
	s_waitcnt lgkmcnt(0)
	v_cvt_pk_bf16_f32 v4, v24, v4
	global_store_dword v[2:3], v4, off offset:128
.LBB0_1690:
	s_or_b64 exec, exec, s[10:11]
	s_waitcnt lgkmcnt(0)
	s_nop 1
	v_mov_b32_dpp v4, v8 quad_perm:[1,0,3,2] row_mask:0xf bank_mask:0xf
	s_and_saveexec_b64 s[10:11], s[4:5]
	s_cbranch_execz .LBB0_1692
	s_waitcnt lgkmcnt(0)
	v_cvt_pk_bf16_f32 v4, v8, v4
	global_store_dword v[2:3], v4, off offset:192
.LBB0_1692:
	s_or_b64 exec, exec, s[10:11]
	s_waitcnt lgkmcnt(0)
	s_nop 1
	v_mov_b32_dpp v4, v57 quad_perm:[1,0,3,2] row_mask:0xf bank_mask:0xf
	v_or_b32_e32 v2, 11, v179
	v_or_b32_e32 v5, s8, v2
	v_lshlrev_b32_e32 v162, 12, v2
	v_cmp_gt_i32_e64 s[10:11], 16, v5
	v_lshl_add_u64 v[2:3], v[66:67], 0, v[162:163]
	s_and_b64 s[4:5], vcc, s[10:11]
	s_and_saveexec_b64 s[10:11], s[4:5]
	s_cbranch_execz .LBB0_1694
	s_waitcnt lgkmcnt(0)
	v_cvt_pk_bf16_f32 v4, v57, v4
	global_store_dword v[2:3], v4, off
.LBB0_1694:
	s_or_b64 exec, exec, s[10:11]
	s_waitcnt lgkmcnt(0)
	s_nop 1
	v_mov_b32_dpp v4, v41 quad_perm:[1,0,3,2] row_mask:0xf bank_mask:0xf
	s_and_saveexec_b64 s[10:11], s[4:5]
	s_cbranch_execz .LBB0_1696
	s_waitcnt lgkmcnt(0)
	v_cvt_pk_bf16_f32 v4, v41, v4
	global_store_dword v[2:3], v4, off offset:64
; __device__ __forceinline__ unsigned cvt_pk_bf16(float lo, float hi) { unsigned r; asm volatile("v_cvt_pk_bf16_f32 %0, %1, %2" : "=v"(r) : "v"(lo), "v"(hi)); return r; }
; __device__ __forceinline__ int crow(int r, int hi) { return (r & 3) + 8 * (r >> 2) + 4 * hi; }
; template <int MODE, bool SAMPLE>
; __device__ __forceinline__ void unit(LAS char* lds, const UnitDesc& D) {
;     ...
;         bf16* Ow = D.O + (size_t)(wid * 32) * DM;
; #pragma unroll
;         for (int r = 0; r < 16; ++r) { const int orow = crow(r, hi);
; #pragma unroll
;             for (int d0 = 0; d0 < 4; ++d0) { const float v = MODE == 0 ? o[d0][r] * rli[r] : o[d0][r];
;                 const float vn = __shfl_xor(v, 1);
;                 if ((r32 & 1) == 0 && wid * 32 + orow < D.nq) *(unsigned*)(Ow + (size_t)orow * DM + d0 * 32 + r32) = cvt_pk_bf16(v, vn); } }
.LBB0_1696:
	s_or_b64 exec, exec, s[10:11]
	s_waitcnt lgkmcnt(0)
	s_nop 1
	v_mov_b32_dpp v4, v25 quad_perm:[1,0,3,2] row_mask:0xf bank_mask:0xf
	s_and_saveexec_b64 s[10:11], s[4:5]
	s_cbranch_execz .LBB0_1698
	s_waitcnt lgkmcnt(0)
	v_cvt_pk_bf16_f32 v4, v25, v4
	global_store_dword v[2:3], v4, off offset:128
.LBB0_1698:
	s_or_b64 exec, exec, s[10:11]
	s_waitcnt lgkmcnt(0)
	s_nop 1
	v_mov_b32_dpp v4, v9 quad_perm:[1,0,3,2] row_mask:0xf bank_mask:0xf
	s_and_saveexec_b64 s[10:11], s[4:5]
	s_cbranch_execz .LBB0_1700
	s_waitcnt lgkmcnt(0)
	v_cvt_pk_bf16_f32 v4, v9, v4
	global_store_dword v[2:3], v4, off offset:192
.LBB0_1700:
	s_or_b64 exec, exec, s[10:11]
	s_waitcnt lgkmcnt(0)
	s_nop 1
	v_mov_b32_dpp v4, v58 quad_perm:[1,0,3,2] row_mask:0xf bank_mask:0xf
	v_or_b32_e32 v2, 16, v179
	v_or_b32_e32 v5, s8, v2
	v_lshlrev_b32_e32 v162, 12, v2
	v_cmp_gt_i32_e64 s[10:11], 16, v5
	v_lshl_add_u64 v[2:3], v[66:67], 0, v[162:163]
	s_and_b64 s[4:5], vcc, s[10:11]
	s_and_saveexec_b64 s[10:11], s[4:5]
	s_cbranch_execz .LBB0_1702
	s_waitcnt lgkmcnt(0)
	v_cvt_pk_bf16_f32 v4, v58, v4
	global_store_dword v[2:3], v4, off
.LBB0_1702:
	s_or_b64 exec, exec, s[10:11]
	s_waitcnt lgkmcnt(0)
	s_nop 1
	v_mov_b32_dpp v4, v42 quad_perm:[1,0,3,2] row_mask:0xf bank_mask:0xf
	s_and_saveexec_b64 s[10:11], s[4:5]
	s_cbranch_execz .LBB0_1704
	s_waitcnt lgkmcnt(0)
	v_cvt_pk_bf16_f32 v4, v42, v4
	global_store_dword v[2:3], v4, off offset:64
.LBB0_1704:
	s_or_b64 exec, exec, s[10:11]
	s_waitcnt lgkmcnt(0)
	s_nop 1
	v_mov_b32_dpp v4, v26 quad_perm:[1,0,3,2] row_mask:0xf bank_mask:0xf
	s_and_saveexec_b64 s[10:11], s[4:5]
	s_cbranch_execz .LBB0_1706
	s_waitcnt lgkmcnt(0)
	v_cvt_pk_bf16_f32 v4, v26, v4
	global_store_dword v[2:3], v4, off offset:128
.LBB0_1706:
	s_or_b64 exec, exec, s[10:11]
	s_waitcnt lgkmcnt(0)
	s_nop 1
	v_mov_b32_dpp v4, v10 quad_perm:[1,0,3,2] row_mask:0xf bank_mask:0xf
	s_and_saveexec_b64 s[10:11], s[4:5]
	s_cbranch_execz .LBB0_1708
	s_waitcnt lgkmcnt(0)
	v_cvt_pk_bf16_f32 v4, v10, v4
	global_store_dword v[2:3], v4, off offset:192
.LBB0_1708:
	s_or_b64 exec, exec, s[10:11]
	s_waitcnt lgkmcnt(0)
	s_nop 1
	v_mov_b32_dpp v4, v59 quad_perm:[1,0,3,2] row_mask:0xf bank_mask:0xf
	v_or_b32_e32 v2, 17, v179
	v_or_b32_e32 v5, s8, v2
	v_lshlrev_b32_e32 v162, 12, v2
	v_cmp_gt_i32_e64 s[10:11], 16, v5
	v_lshl_add_u64 v[2:3], v[66:67], 0, v[162:163]
	s_and_b64 s[4:5], vcc, s[10:11]
	s_and_saveexec_b64 s[10:11], s[4:5]
	s_cbranch_execz .LBB0_1710
	s_waitcnt lgkmcnt(0)
	v_cvt_pk_bf16_f32 v4, v59, v4
	global_store_dword v[2:3], v4, off
.LBB0_1710:
	s_or_b64 exec, exec, s[10:11]
	s_waitcnt lgkmcnt(0)
	s_nop 1
	v_mov_b32_dpp v4, v43 quad_perm:[1,0,3,2] row_mask:0xf bank_mask:0xf
	s_and_saveexec_b64 s[10:11], s[4:5]
	s_cbranch_execz .LBB0_1712
	s_waitcnt lgkmcnt(0)
	v_cvt_pk_bf16_f32 v4, v43, v4
	global_store_dword v[2:3], v4, off offset:64
.LBB0_1712:
	s_or_b64 exec, exec, s[10:11]
	s_waitcnt lgkmcnt(0)
	s_nop 1
	v_mov_b32_dpp v4, v27 quad_perm:[1,0,3,2] row_mask:0xf bank_mask:0xf
	s_and_saveexec_b64 s[10:11], s[4:5]
	s_cbranch_execz .LBB0_1714
	s_waitcnt lgkmcnt(0)
	v_cvt_pk_bf16_f32 v4, v27, v4
	global_store_dword v[2:3], v4, off offset:128
.LBB0_1714:
	s_or_b64 exec, exec, s[10:11]
	s_waitcnt lgkmcnt(0)
	s_nop 1
	v_mov_b32_dpp v4, v11 quad_perm:[1,0,3,2] row_mask:0xf bank_mask:0xf
	s_and_saveexec_b64 s[10:11], s[4:5]
	s_cbranch_execz .LBB0_1716
	s_waitcnt lgkmcnt(0)
	v_cvt_pk_bf16_f32 v4, v11, v4
	global_store_dword v[2:3], v4, off offset:192
.LBB0_1716:
	s_or_b64 exec, exec, s[10:11]
	s_waitcnt lgkmcnt(0)
	s_nop 1
	v_mov_b32_dpp v4, v60 quad_perm:[1,0,3,2] row_mask:0xf bank_mask:0xf
	v_or_b32_e32 v2, 18, v179
	v_or_b32_e32 v5, s8, v2
	v_lshlrev_b32_e32 v162, 12, v2
	v_cmp_gt_i32_e64 s[10:11], 16, v5
	v_lshl_add_u64 v[2:3], v[66:67], 0, v[162:163]
	s_and_b64 s[4:5], vcc, s[10:11]
	s_and_saveexec_b64 s[10:11], s[4:5]
	s_cbranch_execz .LBB0_1718
	s_waitcnt lgkmcnt(0)
	v_cvt_pk_bf16_f32 v4, v60, v4
	global_store_dword v[2:3], v4, off
.LBB0_1718:
	s_or_b64 exec, exec, s[10:11]
	s_waitcnt lgkmcnt(0)
	s_nop 1
	v_mov_b32_dpp v4, v44 quad_perm:[1,0,3,2] row_mask:0xf bank_mask:0xf
	s_and_saveexec_b64 s[10:11], s[4:5]
	s_cbranch_execz .LBB0_1720
	s_waitcnt lgkmcnt(0)
	v_cvt_pk_bf16_f32 v4, v44, v4
	global_store_dword v[2:3], v4, off offset:64
.LBB0_1720:
	s_or_b64 exec, exec, s[10:11]
	s_waitcnt lgkmcnt(0)
	s_nop 1
	v_mov_b32_dpp v4, v28 quad_perm:[1,0,3,2] row_mask:0xf bank_mask:0xf
	s_and_saveexec_b64 s[10:11], s[4:5]
	s_cbranch_execz .LBB0_1722
	s_waitcnt lgkmcnt(0)
	v_cvt_pk_bf16_f32 v4, v28, v4
	global_store_dword v[2:3], v4, off offset:128
.LBB0_1722:
	s_or_b64 exec, exec, s[10:11]
	s_waitcnt lgkmcnt(0)
	s_nop 1
	v_mov_b32_dpp v4, v12 quad_perm:[1,0,3,2] row_mask:0xf bank_mask:0xf
	s_and_saveexec_b64 s[10:11], s[4:5]
	s_cbranch_execz .LBB0_1724
	s_waitcnt lgkmcnt(0)
	v_cvt_pk_bf16_f32 v4, v12, v4
	global_store_dword v[2:3], v4, off offset:192
.LBB0_1724:
	s_or_b64 exec, exec, s[10:11]
	s_waitcnt lgkmcnt(0)
	s_nop 1
	v_mov_b32_dpp v4, v61 quad_perm:[1,0,3,2] row_mask:0xf bank_mask:0xf
	v_or_b32_e32 v2, 19, v179
	v_or_b32_e32 v5, s8, v2
	v_lshlrev_b32_e32 v162, 12, v2
	v_cmp_gt_i32_e64 s[10:11], 16, v5
	v_lshl_add_u64 v[2:3], v[66:67], 0, v[162:163]
	s_and_b64 s[4:5], vcc, s[10:11]
	s_and_saveexec_b64 s[10:11], s[4:5]
	s_cbranch_execz .LBB0_1726
	s_waitcnt lgkmcnt(0)
	v_cvt_pk_bf16_f32 v4, v61, v4
	global_store_dword v[2:3], v4, off
.LBB0_1726:
	s_or_b64 exec, exec, s[10:11]
	s_waitcnt lgkmcnt(0)
	s_nop 1
	v_mov_b32_dpp v4, v45 quad_perm:[1,0,3,2] row_mask:0xf bank_mask:0xf
	s_and_saveexec_b64 s[10:11], s[4:5]
	s_cbranch_execz .LBB0_1728
	s_waitcnt lgkmcnt(0)
	v_cvt_pk_bf16_f32 v4, v45, v4
	global_store_dword v[2:3], v4, off offset:64
; __device__ __forceinline__ unsigned cvt_pk_bf16(float lo, float hi) { unsigned r; asm volatile("v_cvt_pk_bf16_f32 %0, %1, %2" : "=v"(r) : "v"(lo), "v"(hi)); return r; }
; __device__ __forceinline__ int crow(int r, int hi) { return (r & 3) + 8 * (r >> 2) + 4 * hi; }
; template <int MODE, bool SAMPLE>
; __device__ __forceinline__ void unit(LAS char* lds, const UnitDesc& D) {
;     ...
;         bf16* Ow = D.O + (size_t)(wid * 32) * DM;
; #pragma unroll
;         for (int r = 0; r < 16; ++r) { const int orow = crow(r, hi);
; #pragma unroll
;             for (int d0 = 0; d0 < 4; ++d0) { const float v = MODE == 0 ? o[d0][r] * rli[r] : o[d0][r];
;                 const float vn = __shfl_xor(v, 1);
;                 if ((r32 & 1) == 0 && wid * 32 + orow < D.nq) *(unsigned*)(Ow + (size_t)orow * DM + d0 * 32 + r32) = cvt_pk_bf16(v, vn); } }
.LBB0_1728:
	s_or_b64 exec, exec, s[10:11]
	s_waitcnt lgkmcnt(0)
	s_nop 1
	v_mov_b32_dpp v4, v29 quad_perm:[1,0,3,2] row_mask:0xf bank_mask:0xf
	s_and_saveexec_b64 s[10:11], s[4:5]
	s_cbranch_execz .LBB0_1730
	s_waitcnt lgkmcnt(0)
	v_cvt_pk_bf16_f32 v4, v29, v4
	global_store_dword v[2:3], v4, off offset:128
.LBB0_1730:
	s_or_b64 exec, exec, s[10:11]
	s_waitcnt lgkmcnt(0)
	s_nop 1
	v_mov_b32_dpp v4, v13 quad_perm:[1,0,3,2] row_mask:0xf bank_mask:0xf
	s_and_saveexec_b64 s[10:11], s[4:5]
	s_cbranch_execz .LBB0_1732
	s_waitcnt lgkmcnt(0)
	v_cvt_pk_bf16_f32 v4, v13, v4
	global_store_dword v[2:3], v4, off offset:192
.LBB0_1732:
	s_or_b64 exec, exec, s[10:11]
	s_waitcnt lgkmcnt(0)
	s_nop 1
	v_mov_b32_dpp v4, v62 quad_perm:[1,0,3,2] row_mask:0xf bank_mask:0xf
	v_or_b32_e32 v2, 24, v179
	v_or_b32_e32 v5, s8, v2
	v_lshlrev_b32_e32 v162, 12, v2
	v_cmp_gt_i32_e64 s[10:11], 16, v5
	v_lshl_add_u64 v[2:3], v[66:67], 0, v[162:163]
	s_and_b64 s[4:5], vcc, s[10:11]
	s_and_saveexec_b64 s[10:11], s[4:5]
	s_cbranch_execz .LBB0_1734
	s_waitcnt lgkmcnt(0)
	v_cvt_pk_bf16_f32 v4, v62, v4
	global_store_dword v[2:3], v4, off
.LBB0_1734:
	s_or_b64 exec, exec, s[10:11]
	s_waitcnt lgkmcnt(0)
	s_nop 1
	v_mov_b32_dpp v4, v46 quad_perm:[1,0,3,2] row_mask:0xf bank_mask:0xf
	s_and_saveexec_b64 s[10:11], s[4:5]
	s_cbranch_execz .LBB0_1736
	s_waitcnt lgkmcnt(0)
	v_cvt_pk_bf16_f32 v4, v46, v4
	global_store_dword v[2:3], v4, off offset:64
.LBB0_1736:
	s_or_b64 exec, exec, s[10:11]
	s_waitcnt lgkmcnt(0)
	s_nop 1
	v_mov_b32_dpp v4, v30 quad_perm:[1,0,3,2] row_mask:0xf bank_mask:0xf
	s_and_saveexec_b64 s[10:11], s[4:5]
	s_cbranch_execz .LBB0_1738
	s_waitcnt lgkmcnt(0)
	v_cvt_pk_bf16_f32 v4, v30, v4
	global_store_dword v[2:3], v4, off offset:128
.LBB0_1738:
	s_or_b64 exec, exec, s[10:11]
	s_waitcnt lgkmcnt(0)
	s_nop 1
	v_mov_b32_dpp v4, v14 quad_perm:[1,0,3,2] row_mask:0xf bank_mask:0xf
	s_and_saveexec_b64 s[10:11], s[4:5]
	s_cbranch_execz .LBB0_1740
	s_waitcnt lgkmcnt(0)
	v_cvt_pk_bf16_f32 v4, v14, v4
	global_store_dword v[2:3], v4, off offset:192
.LBB0_1740:
	s_or_b64 exec, exec, s[10:11]
	s_waitcnt lgkmcnt(0)
	s_nop 1
	v_mov_b32_dpp v4, v63 quad_perm:[1,0,3,2] row_mask:0xf bank_mask:0xf
	v_or_b32_e32 v2, 25, v179
	v_or_b32_e32 v5, s8, v2
	v_lshlrev_b32_e32 v162, 12, v2
	v_cmp_gt_i32_e64 s[10:11], 16, v5
	v_lshl_add_u64 v[2:3], v[66:67], 0, v[162:163]
	s_and_b64 s[4:5], vcc, s[10:11]
	s_and_saveexec_b64 s[10:11], s[4:5]
	s_cbranch_execz .LBB0_1742
	s_waitcnt lgkmcnt(0)
	v_cvt_pk_bf16_f32 v4, v63, v4
	global_store_dword v[2:3], v4, off
.LBB0_1742:
	s_or_b64 exec, exec, s[10:11]
	s_waitcnt lgkmcnt(0)
	s_nop 1
	v_mov_b32_dpp v4, v47 quad_perm:[1,0,3,2] row_mask:0xf bank_mask:0xf
	s_and_saveexec_b64 s[10:11], s[4:5]
	s_cbranch_execz .LBB0_1744
	s_waitcnt lgkmcnt(0)
	v_cvt_pk_bf16_f32 v4, v47, v4
	global_store_dword v[2:3], v4, off offset:64
.LBB0_1744:
	s_or_b64 exec, exec, s[10:11]
	s_waitcnt lgkmcnt(0)
	s_nop 1
	v_mov_b32_dpp v4, v31 quad_perm:[1,0,3,2] row_mask:0xf bank_mask:0xf
	s_and_saveexec_b64 s[10:11], s[4:5]
	s_cbranch_execz .LBB0_1746
	s_waitcnt lgkmcnt(0)
	v_cvt_pk_bf16_f32 v4, v31, v4
	global_store_dword v[2:3], v4, off offset:128
.LBB0_1746:
	s_or_b64 exec, exec, s[10:11]
	s_waitcnt lgkmcnt(0)
	s_nop 1
	v_mov_b32_dpp v4, v15 quad_perm:[1,0,3,2] row_mask:0xf bank_mask:0xf
	s_and_saveexec_b64 s[10:11], s[4:5]
	s_cbranch_execz .LBB0_1748
	s_waitcnt lgkmcnt(0)
	v_cvt_pk_bf16_f32 v4, v15, v4
	global_store_dword v[2:3], v4, off offset:192
.LBB0_1748:
	s_or_b64 exec, exec, s[10:11]
	s_waitcnt lgkmcnt(0)
	s_nop 1
	v_mov_b32_dpp v4, v64 quad_perm:[1,0,3,2] row_mask:0xf bank_mask:0xf
	v_or_b32_e32 v2, 26, v179
	v_or_b32_e32 v5, s8, v2
	v_lshlrev_b32_e32 v162, 12, v2
	v_cmp_gt_i32_e64 s[10:11], 16, v5
	v_lshl_add_u64 v[2:3], v[66:67], 0, v[162:163]
	s_and_b64 s[4:5], vcc, s[10:11]
	s_and_saveexec_b64 s[10:11], s[4:5]
	s_cbranch_execz .LBB0_1750
	s_waitcnt lgkmcnt(0)
	v_cvt_pk_bf16_f32 v4, v64, v4
	global_store_dword v[2:3], v4, off
.LBB0_1750:
	s_or_b64 exec, exec, s[10:11]
	s_waitcnt lgkmcnt(0)
	s_nop 1
	v_mov_b32_dpp v4, v48 quad_perm:[1,0,3,2] row_mask:0xf bank_mask:0xf
	s_and_saveexec_b64 s[10:11], s[4:5]
	s_cbranch_execz .LBB0_1752
	s_waitcnt lgkmcnt(0)
	v_cvt_pk_bf16_f32 v4, v48, v4
	global_store_dword v[2:3], v4, off offset:64
.LBB0_1752:
	s_or_b64 exec, exec, s[10:11]
	s_waitcnt lgkmcnt(0)
	s_nop 1
	v_mov_b32_dpp v4, v32 quad_perm:[1,0,3,2] row_mask:0xf bank_mask:0xf
	s_and_saveexec_b64 s[10:11], s[4:5]
	s_cbranch_execz .LBB0_1754
	s_waitcnt lgkmcnt(0)
	v_cvt_pk_bf16_f32 v4, v32, v4
	global_store_dword v[2:3], v4, off offset:128
.LBB0_1754:
	s_or_b64 exec, exec, s[10:11]
	s_waitcnt lgkmcnt(0)
	s_nop 1
	v_mov_b32_dpp v4, v16 quad_perm:[1,0,3,2] row_mask:0xf bank_mask:0xf
	s_and_saveexec_b64 s[10:11], s[4:5]
	s_cbranch_execz .LBB0_1756
	s_waitcnt lgkmcnt(0)
	v_cvt_pk_bf16_f32 v4, v16, v4
	global_store_dword v[2:3], v4, off offset:192
.LBB0_1756:
	s_or_b64 exec, exec, s[10:11]
	s_waitcnt lgkmcnt(0)
	s_nop 1
	v_mov_b32_dpp v4, v65 quad_perm:[1,0,3,2] row_mask:0xf bank_mask:0xf
	v_or_b32_e32 v2, 27, v179
	v_or_b32_e32 v5, s8, v2
	v_lshlrev_b32_e32 v162, 12, v2
	v_cmp_gt_i32_e64 s[10:11], 16, v5
	v_lshl_add_u64 v[2:3], v[66:67], 0, v[162:163]
	s_and_b64 s[4:5], vcc, s[10:11]
	s_and_saveexec_b64 s[8:9], s[4:5]
	s_cbranch_execz .LBB0_1758
	s_waitcnt lgkmcnt(0)
	v_cvt_pk_bf16_f32 v4, v65, v4
	global_store_dword v[2:3], v4, off
.LBB0_1758:
	s_or_b64 exec, exec, s[8:9]
	s_waitcnt lgkmcnt(0)
	s_nop 1
	v_mov_b32_dpp v4, v49 quad_perm:[1,0,3,2] row_mask:0xf bank_mask:0xf
	s_and_saveexec_b64 s[8:9], s[4:5]
	s_cbranch_execz .LBB0_1760
	s_waitcnt lgkmcnt(0)
	v_cvt_pk_bf16_f32 v4, v49, v4
	global_store_dword v[2:3], v4, off offset:64
.LBB0_1760:
	s_or_b64 exec, exec, s[8:9]
	s_waitcnt lgkmcnt(0)
	s_nop 1
	v_mov_b32_dpp v4, v33 quad_perm:[1,0,3,2] row_mask:0xf bank_mask:0xf
	s_and_saveexec_b64 s[8:9], s[4:5]
	s_cbranch_execz .LBB0_1762
	s_waitcnt lgkmcnt(0)
	v_cvt_pk_bf16_f32 v4, v33, v4
	global_store_dword v[2:3], v4, off offset:128
.LBB0_1762:
	s_or_b64 exec, exec, s[8:9]
	s_waitcnt lgkmcnt(0)
	s_nop 1
	v_mov_b32_dpp v4, v17 quad_perm:[1,0,3,2] row_mask:0xf bank_mask:0xf
	s_and_saveexec_b64 s[8:9], s[4:5]
	s_cbranch_execz .LBB0_1764
	s_waitcnt lgkmcnt(0)
	v_cvt_pk_bf16_f32 v4, v17, v4
	global_store_dword v[2:3], v4, off offset:192

; __device__ __forceinline__ unsigned cvt_pk_bf16(float lo, float hi) { unsigned r; asm volatile("v_cvt_pk_bf16_f32 %0, %1, %2" : "=v"(r) : "v"(lo), "v"(hi)); return r; }
; __device__ __forceinline__ int crow(int r, int hi) { return (r & 3) + 8 * (r >> 2) + 4 * hi; }
; template <int MODE, bool SAMPLE>
; __device__ __forceinline__ void unit(LAS char* lds, const UnitDesc& D) {
;     ...
;         bf16* Ow = D.O + (size_t)(wid * 32) * DM;
; #pragma unroll
;         for (int r = 0; r < 16; ++r) { const int orow = crow(r, hi);
; #pragma unroll
;             for (int d0 = 0; d0 < 4; ++d0) { const float v = MODE == 0 ? o[d0][r] * rli[r] : o[d0][r];
;                 const float vn = __shfl_xor(v, 1);
;                 if ((r32 & 1) == 0 && wid * 32 + orow < D.nq) *(unsigned*)(Ow + (size_t)orow * DM + d0 * 32 + r32) = cvt_pk_bf16(v, vn); } }
.LBB0_1782:
	s_andn2_b64 vcc, exec, s[80:81]
	s_cbranch_vccnz .LBB0_1609
	s_lshl_b32 s2, s6, 1
	s_add_u32 s2, s4, s2
	v_and_b32_e32 v67, 64, v202
	s_addc_u32 s3, s5, 0
	s_lshl_b32 s4, s7, 1
	v_xor_b32_e32 v66, 1, v202
	v_add_u32_e32 v67, 64, v67
	s_add_u32 s4, s2, s4
	v_cmp_lt_i32_e32 vcc, v66, v67
	s_addc_u32 s5, s3, 0
	s_ashr_i32 s9, s8, 31
	v_cndmask_b32_e32 v66, v202, v66, vcc
	s_lshl_b64 s[2:3], s[8:9], 12
	v_lshlrev_b32_e32 v70, 2, v66
	s_add_u32 s2, s4, s2
	s_nop 1
	v_mov_b32_dpp v71, v50 quad_perm:[1,0,3,2] row_mask:0xf bank_mask:0xf
	s_addc_u32 s3, s5, s3
	v_and_b32_e32 v66, 1, v190
	v_lshlrev_b32_e32 v162, 1, v192
	v_cmp_eq_u32_e32 vcc, 0, v66
	v_lshl_add_u64 v[66:67], s[2:3], 0, v[162:163]
	s_mov_b64 s[2:3], 0x17500000
	v_or_b32_e32 v72, s8, v179
	s_movk_i32 s6, 0x100
	v_lshl_add_u64 v[66:67], v[66:67], 0, s[2:3]
	v_lshlrev_b32_e32 v162, 14, v191
	v_cmp_gt_i32_e64 s[10:11], s6, v72
	v_lshl_add_u64 v[68:69], v[66:67], 0, v[162:163]
	s_and_b64 s[4:5], vcc, s[10:11]
	s_and_saveexec_b64 s[10:11], s[4:5]
	s_cbranch_execz .LBB0_1785
	s_waitcnt lgkmcnt(0)
	v_cvt_pk_bf16_f32 v50, v50, v71
	global_store_dword v[68:69], v50, off

; __device__ __forceinline__ unsigned cvt_pk_bf16(float lo, float hi) { unsigned r; asm volatile("v_cvt_pk_bf16_f32 %0, %1, %2" : "=v"(r) : "v"(lo), "v"(hi)); return r; }
; __device__ __forceinline__ int crow(int r, int hi) { return (r & 3) + 8 * (r >> 2) + 4 * hi; }
; template <int MODE, bool SAMPLE>
; __device__ __forceinline__ void unit(LAS char* lds, const UnitDesc& D) {
;     ...
;         bf16* Ow = D.O + (size_t)(wid * 32) * DM;
; #pragma unroll
;         for (int r = 0; r < 16; ++r) { const int orow = crow(r, hi);
; #pragma unroll
;             for (int d0 = 0; d0 < 4; ++d0) { const float v = MODE == 0 ? o[d0][r] * rli[r] : o[d0][r];
;                 const float vn = __shfl_xor(v, 1);
;                 if ((r32 & 1) == 0 && wid * 32 + orow < D.nq) *(unsigned*)(Ow + (size_t)orow * DM + d0 * 32 + r32) = cvt_pk_bf16(v, vn); } }
.LBB0_1791:
	s_or_b64 exec, exec, s[10:11]
	s_nop 1
	v_mov_b32_dpp v2, v51 quad_perm:[1,0,3,2] row_mask:0xf bank_mask:0xf
	s_waitcnt lgkmcnt(0)
	v_or_b32_e32 v18, 1, v179
	v_or_b32_e32 v34, s8, v18
	v_lshlrev_b32_e32 v162, 12, v18
	v_cmp_gt_i32_e64 s[10:11], s6, v34
	v_lshl_add_u64 v[68:69], v[66:67], 0, v[162:163]
	s_and_b64 s[4:5], vcc, s[10:11]
	s_and_saveexec_b64 s[10:11], s[4:5]
	s_cbranch_execz .LBB0_1793
	s_waitcnt lgkmcnt(0)
	v_cvt_pk_bf16_f32 v2, v51, v2
	global_store_dword v[68:69], v2, off

; __device__ __forceinline__ unsigned cvt_pk_bf16(float lo, float hi) { unsigned r; asm volatile("v_cvt_pk_bf16_f32 %0, %1, %2" : "=v"(r) : "v"(lo), "v"(hi)); return r; }
; __device__ __forceinline__ int crow(int r, int hi) { return (r & 3) + 8 * (r >> 2) + 4 * hi; }
; template <int MODE, bool SAMPLE>
; __device__ __forceinline__ void unit(LAS char* lds, const UnitDesc& D) {
;     ...
;         bf16* Ow = D.O + (size_t)(wid * 32) * DM;
; #pragma unroll
;         for (int r = 0; r < 16; ++r) { const int orow = crow(r, hi);
; #pragma unroll
;             for (int d0 = 0; d0 < 4; ++d0) { const float v = MODE == 0 ? o[d0][r] * rli[r] : o[d0][r];
;                 const float vn = __shfl_xor(v, 1);
;                 if ((r32 & 1) == 0 && wid * 32 + orow < D.nq) *(unsigned*)(Ow + (size_t)orow * DM + d0 * 32 + r32) = cvt_pk_bf16(v, vn); } }
.LBB0_1799:
	s_or_b64 exec, exec, s[10:11]
	s_nop 1
	v_mov_b32_dpp v18, v52 quad_perm:[1,0,3,2] row_mask:0xf bank_mask:0xf
	s_waitcnt lgkmcnt(0)
	v_or_b32_e32 v2, 2, v179
	v_or_b32_e32 v19, s8, v2
	v_lshlrev_b32_e32 v162, 12, v2
	v_cmp_gt_i32_e64 s[10:11], s6, v19
	v_lshl_add_u64 v[2:3], v[66:67], 0, v[162:163]
	s_and_b64 s[4:5], vcc, s[10:11]
	s_and_saveexec_b64 s[10:11], s[4:5]
	s_cbranch_execz .LBB0_1801
	s_waitcnt lgkmcnt(0)
	v_cvt_pk_bf16_f32 v18, v52, v18
	global_store_dword v[2:3], v18, off

; __device__ __forceinline__ unsigned cvt_pk_bf16(float lo, float hi) { unsigned r; asm volatile("v_cvt_pk_bf16_f32 %0, %1, %2" : "=v"(r) : "v"(lo), "v"(hi)); return r; }
; __device__ __forceinline__ int crow(int r, int hi) { return (r & 3) + 8 * (r >> 2) + 4 * hi; }
; template <int MODE, bool SAMPLE>
; __device__ __forceinline__ void unit(LAS char* lds, const UnitDesc& D) {
;     ...
;         bf16* Ow = D.O + (size_t)(wid * 32) * DM;
; #pragma unroll
;         for (int r = 0; r < 16; ++r) { const int orow = crow(r, hi);
; #pragma unroll
;             for (int d0 = 0; d0 < 4; ++d0) { const float v = MODE == 0 ? o[d0][r] * rli[r] : o[d0][r];
;                 const float vn = __shfl_xor(v, 1);
;                 if ((r32 & 1) == 0 && wid * 32 + orow < D.nq) *(unsigned*)(Ow + (size_t)orow * DM + d0 * 32 + r32) = cvt_pk_bf16(v, vn); } }
.LBB0_1807:
	s_or_b64 exec, exec, s[10:11]
	s_nop 1
	v_mov_b32_dpp v4, v53 quad_perm:[1,0,3,2] row_mask:0xf bank_mask:0xf
	v_or_b32_e32 v2, 3, v179
	s_waitcnt lgkmcnt(0)
	v_or_b32_e32 v18, s8, v2
	v_lshlrev_b32_e32 v162, 12, v2
	v_cmp_gt_i32_e64 s[10:11], s6, v18
	v_lshl_add_u64 v[2:3], v[66:67], 0, v[162:163]
	s_and_b64 s[4:5], vcc, s[10:11]
	s_and_saveexec_b64 s[10:11], s[4:5]
	s_cbranch_execz .LBB0_1809
	s_waitcnt lgkmcnt(0)
	v_cvt_pk_bf16_f32 v4, v53, v4
	global_store_dword v[2:3], v4, off

; __device__ __forceinline__ unsigned cvt_pk_bf16(float lo, float hi) { unsigned r; asm volatile("v_cvt_pk_bf16_f32 %0, %1, %2" : "=v"(r) : "v"(lo), "v"(hi)); return r; }
; __device__ __forceinline__ int crow(int r, int hi) { return (r & 3) + 8 * (r >> 2) + 4 * hi; }
; template <int MODE, bool SAMPLE>
; __device__ __forceinline__ void unit(LAS char* lds, const UnitDesc& D) {
;     ...
;         bf16* Ow = D.O + (size_t)(wid * 32) * DM;
; #pragma unroll
;         for (int r = 0; r < 16; ++r) { const int orow = crow(r, hi);
; #pragma unroll
;             for (int d0 = 0; d0 < 4; ++d0) { const float v = MODE == 0 ? o[d0][r] * rli[r] : o[d0][r];
;                 const float vn = __shfl_xor(v, 1);
;                 if ((r32 & 1) == 0 && wid * 32 + orow < D.nq) *(unsigned*)(Ow + (size_t)orow * DM + d0 * 32 + r32) = cvt_pk_bf16(v, vn); } }
.LBB0_1815:
	s_or_b64 exec, exec, s[10:11]
	s_waitcnt lgkmcnt(0)
	s_nop 1
	v_mov_b32_dpp v4, v54 quad_perm:[1,0,3,2] row_mask:0xf bank_mask:0xf
	v_or_b32_e32 v2, 8, v179
	v_or_b32_e32 v5, s8, v2
	v_lshlrev_b32_e32 v162, 12, v2
	v_cmp_gt_i32_e64 s[10:11], s6, v5
	v_lshl_add_u64 v[2:3], v[66:67], 0, v[162:163]
	s_and_b64 s[4:5], vcc, s[10:11]
	s_and_saveexec_b64 s[10:11], s[4:5]
	s_cbranch_execz .LBB0_1817
	s_waitcnt lgkmcnt(0)
	v_cvt_pk_bf16_f32 v4, v54, v4
	global_store_dword v[2:3], v4, off

; __device__ __forceinline__ unsigned cvt_pk_bf16(float lo, float hi) { unsigned r; asm volatile("v_cvt_pk_bf16_f32 %0, %1, %2" : "=v"(r) : "v"(lo), "v"(hi)); return r; }
; __device__ __forceinline__ int crow(int r, int hi) { return (r & 3) + 8 * (r >> 2) + 4 * hi; }
; template <int MODE, bool SAMPLE>
; __device__ __forceinline__ void unit(LAS char* lds, const UnitDesc& D) {
;     ...
;         bf16* Ow = D.O + (size_t)(wid * 32) * DM;
; #pragma unroll
;         for (int r = 0; r < 16; ++r) { const int orow = crow(r, hi);
; #pragma unroll
;             for (int d0 = 0; d0 < 4; ++d0) { const float v = MODE == 0 ? o[d0][r] * rli[r] : o[d0][r];
;                 const float vn = __shfl_xor(v, 1);
;                 if ((r32 & 1) == 0 && wid * 32 + orow < D.nq) *(unsigned*)(Ow + (size_t)orow * DM + d0 * 32 + r32) = cvt_pk_bf16(v, vn); } }
.LBB0_1823:
	s_or_b64 exec, exec, s[10:11]
	s_waitcnt lgkmcnt(0)
	s_nop 1
	v_mov_b32_dpp v4, v55 quad_perm:[1,0,3,2] row_mask:0xf bank_mask:0xf
	v_or_b32_e32 v2, 9, v179
	v_or_b32_e32 v5, s8, v2
	v_lshlrev_b32_e32 v162, 12, v2
	v_cmp_gt_i32_e64 s[10:11], s6, v5
	v_lshl_add_u64 v[2:3], v[66:67], 0, v[162:163]
	s_and_b64 s[4:5], vcc, s[10:11]
	s_and_saveexec_b64 s[10:11], s[4:5]
	s_cbranch_execz .LBB0_1825
	s_waitcnt lgkmcnt(0)
	v_cvt_pk_bf16_f32 v4, v55, v4
	global_store_dword v[2:3], v4, off

; __device__ __forceinline__ unsigned cvt_pk_bf16(float lo, float hi) { unsigned r; asm volatile("v_cvt_pk_bf16_f32 %0, %1, %2" : "=v"(r) : "v"(lo), "v"(hi)); return r; }
; __device__ __forceinline__ int crow(int r, int hi) { return (r & 3) + 8 * (r >> 2) + 4 * hi; }
; template <int MODE, bool SAMPLE>
; __device__ __forceinline__ void unit(LAS char* lds, const UnitDesc& D) {
;     ...
;         bf16* Ow = D.O + (size_t)(wid * 32) * DM;
; #pragma unroll
;         for (int r = 0; r < 16; ++r) { const int orow = crow(r, hi);
; #pragma unroll
;             for (int d0 = 0; d0 < 4; ++d0) { const float v = MODE == 0 ? o[d0][r] * rli[r] : o[d0][r];
;                 const float vn = __shfl_xor(v, 1);
;                 if ((r32 & 1) == 0 && wid * 32 + orow < D.nq) *(unsigned*)(Ow + (size_t)orow * DM + d0 * 32 + r32) = cvt_pk_bf16(v, vn); } }
.LBB0_1831:
	s_or_b64 exec, exec, s[10:11]
	s_waitcnt lgkmcnt(0)
	s_nop 1
	v_mov_b32_dpp v4, v56 quad_perm:[1,0,3,2] row_mask:0xf bank_mask:0xf
	v_or_b32_e32 v2, 10, v179
	v_or_b32_e32 v5, s8, v2
	v_lshlrev_b32_e32 v162, 12, v2
	v_cmp_gt_i32_e64 s[10:11], s6, v5
	v_lshl_add_u64 v[2:3], v[66:67], 0, v[162:163]
	s_and_b64 s[4:5], vcc, s[10:11]
	s_and_saveexec_b64 s[10:11], s[4:5]
	s_cbranch_execz .LBB0_1833
	s_waitcnt lgkmcnt(0)
	v_cvt_pk_bf16_f32 v4, v56, v4
	global_store_dword v[2:3], v4, off

; __device__ __forceinline__ unsigned cvt_pk_bf16(float lo, float hi) { unsigned r; asm volatile("v_cvt_pk_bf16_f32 %0, %1, %2" : "=v"(r) : "v"(lo), "v"(hi)); return r; }
; __device__ __forceinline__ int crow(int r, int hi) { return (r & 3) + 8 * (r >> 2) + 4 * hi; }
; template <int MODE, bool SAMPLE>
; __device__ __forceinline__ void unit(LAS char* lds, const UnitDesc& D) {
;     ...
;         bf16* Ow = D.O + (size_t)(wid * 32) * DM;
; #pragma unroll
;         for (int r = 0; r < 16; ++r) { const int orow = crow(r, hi);
; #pragma unroll
;             for (int d0 = 0; d0 < 4; ++d0) { const float v = MODE == 0 ? o[d0][r] * rli[r] : o[d0][r];
;                 const float vn = __shfl_xor(v, 1);
;                 if ((r32 & 1) == 0 && wid * 32 + orow < D.nq) *(unsigned*)(Ow + (size_t)orow * DM + d0 * 32 + r32) = cvt_pk_bf16(v, vn); } }
.LBB0_1839:
	s_or_b64 exec, exec, s[10:11]
	s_waitcnt lgkmcnt(0)
	s_nop 1
	v_mov_b32_dpp v4, v57 quad_perm:[1,0,3,2] row_mask:0xf bank_mask:0xf
	v_or_b32_e32 v2, 11, v179
	v_or_b32_e32 v5, s8, v2
	v_lshlrev_b32_e32 v162, 12, v2
	v_cmp_gt_i32_e64 s[10:11], s6, v5
	v_lshl_add_u64 v[2:3], v[66:67], 0, v[162:163]
	s_and_b64 s[4:5], vcc, s[10:11]
	s_and_saveexec_b64 s[10:11], s[4:5]
	s_cbranch_execz .LBB0_1841
	s_waitcnt lgkmcnt(0)
	v_cvt_pk_bf16_f32 v4, v57, v4
	global_store_dword v[2:3], v4, off

; __device__ __forceinline__ unsigned cvt_pk_bf16(float lo, float hi) { unsigned r; asm volatile("v_cvt_pk_bf16_f32 %0, %1, %2" : "=v"(r) : "v"(lo), "v"(hi)); return r; }
; __device__ __forceinline__ int crow(int r, int hi) { return (r & 3) + 8 * (r >> 2) + 4 * hi; }
; template <int MODE, bool SAMPLE>
; __device__ __forceinline__ void unit(LAS char* lds, const UnitDesc& D) {
;     ...
;         bf16* Ow = D.O + (size_t)(wid * 32) * DM;
; #pragma unroll
;         for (int r = 0; r < 16; ++r) { const int orow = crow(r, hi);
; #pragma unroll
;             for (int d0 = 0; d0 < 4; ++d0) { const float v = MODE == 0 ? o[d0][r] * rli[r] : o[d0][r];
;                 const float vn = __shfl_xor(v, 1);
;                 if ((r32 & 1) == 0 && wid * 32 + orow < D.nq) *(unsigned*)(Ow + (size_t)orow * DM + d0 * 32 + r32) = cvt_pk_bf16(v, vn); } }
.LBB0_1847:
	s_or_b64 exec, exec, s[10:11]
	s_waitcnt lgkmcnt(0)
	s_nop 1
	v_mov_b32_dpp v4, v58 quad_perm:[1,0,3,2] row_mask:0xf bank_mask:0xf
	v_or_b32_e32 v2, 16, v179
	v_or_b32_e32 v5, s8, v2
	v_lshlrev_b32_e32 v162, 12, v2
	v_cmp_gt_i32_e64 s[10:11], s6, v5
	v_lshl_add_u64 v[2:3], v[66:67], 0, v[162:163]
	s_and_b64 s[4:5], vcc, s[10:11]
	s_and_saveexec_b64 s[10:11], s[4:5]
	s_cbranch_execz .LBB0_1849
	s_waitcnt lgkmcnt(0)
	v_cvt_pk_bf16_f32 v4, v58, v4
	global_store_dword v[2:3], v4, off

; __device__ __forceinline__ unsigned cvt_pk_bf16(float lo, float hi) { unsigned r; asm volatile("v_cvt_pk_bf16_f32 %0, %1, %2" : "=v"(r) : "v"(lo), "v"(hi)); return r; }
; __device__ __forceinline__ int crow(int r, int hi) { return (r & 3) + 8 * (r >> 2) + 4 * hi; }
; template <int MODE, bool SAMPLE>
; __device__ __forceinline__ void unit(LAS char* lds, const UnitDesc& D) {
;     ...
;         bf16* Ow = D.O + (size_t)(wid * 32) * DM;
; #pragma unroll
;         for (int r = 0; r < 16; ++r) { const int orow = crow(r, hi);
; #pragma unroll
;             for (int d0 = 0; d0 < 4; ++d0) { const float v = MODE == 0 ? o[d0][r] * rli[r] : o[d0][r];
;                 const float vn = __shfl_xor(v, 1);
;                 if ((r32 & 1) == 0 && wid * 32 + orow < D.nq) *(unsigned*)(Ow + (size_t)orow * DM + d0 * 32 + r32) = cvt_pk_bf16(v, vn); } }
.LBB0_1855:
	s_or_b64 exec, exec, s[10:11]
	s_waitcnt lgkmcnt(0)
	s_nop 1
	v_mov_b32_dpp v4, v59 quad_perm:[1,0,3,2] row_mask:0xf bank_mask:0xf
	v_or_b32_e32 v2, 17, v179
	v_or_b32_e32 v5, s8, v2
	v_lshlrev_b32_e32 v162, 12, v2
	v_cmp_gt_i32_e64 s[10:11], s6, v5
	v_lshl_add_u64 v[2:3], v[66:67], 0, v[162:163]
	s_and_b64 s[4:5], vcc, s[10:11]
	s_and_saveexec_b64 s[10:11], s[4:5]
	s_cbranch_execz .LBB0_1857
	s_waitcnt lgkmcnt(0)
	v_cvt_pk_bf16_f32 v4, v59, v4
	global_store_dword v[2:3], v4, off

; __device__ __forceinline__ unsigned cvt_pk_bf16(float lo, float hi) { unsigned r; asm volatile("v_cvt_pk_bf16_f32 %0, %1, %2" : "=v"(r) : "v"(lo), "v"(hi)); return r; }
; __device__ __forceinline__ int crow(int r, int hi) { return (r & 3) + 8 * (r >> 2) + 4 * hi; }
; template <int MODE, bool SAMPLE>
; __device__ __forceinline__ void unit(LAS char* lds, const UnitDesc& D) {
;     ...
;         bf16* Ow = D.O + (size_t)(wid * 32) * DM;
; #pragma unroll
;         for (int r = 0; r < 16; ++r) { const int orow = crow(r, hi);
; #pragma unroll
;             for (int d0 = 0; d0 < 4; ++d0) { const float v = MODE == 0 ? o[d0][r] * rli[r] : o[d0][r];
;                 const float vn = __shfl_xor(v, 1);
;                 if ((r32 & 1) == 0 && wid * 32 + orow < D.nq) *(unsigned*)(Ow + (size_t)orow * DM + d0 * 32 + r32) = cvt_pk_bf16(v, vn); } }
.LBB0_1863:
	s_or_b64 exec, exec, s[10:11]
	s_waitcnt lgkmcnt(0)
	s_nop 1
	v_mov_b32_dpp v4, v60 quad_perm:[1,0,3,2] row_mask:0xf bank_mask:0xf
	v_or_b32_e32 v2, 18, v179
	v_or_b32_e32 v5, s8, v2
	v_lshlrev_b32_e32 v162, 12, v2
	v_cmp_gt_i32_e64 s[10:11], s6, v5
	v_lshl_add_u64 v[2:3], v[66:67], 0, v[162:163]
	s_and_b64 s[4:5], vcc, s[10:11]
	s_and_saveexec_b64 s[10:11], s[4:5]
	s_cbranch_execz .LBB0_1865
	s_waitcnt lgkmcnt(0)
	v_cvt_pk_bf16_f32 v4, v60, v4
	global_store_dword v[2:3], v4, off

; __device__ __forceinline__ unsigned cvt_pk_bf16(float lo, float hi) { unsigned r; asm volatile("v_cvt_pk_bf16_f32 %0, %1, %2" : "=v"(r) : "v"(lo), "v"(hi)); return r; }
; __device__ __forceinline__ int crow(int r, int hi) { return (r & 3) + 8 * (r >> 2) + 4 * hi; }
; template <int MODE, bool SAMPLE>
; __device__ __forceinline__ void unit(LAS char* lds, const UnitDesc& D) {
;     ...
;         bf16* Ow = D.O + (size_t)(wid * 32) * DM;
; #pragma unroll
;         for (int r = 0; r < 16; ++r) { const int orow = crow(r, hi);
; #pragma unroll
;             for (int d0 = 0; d0 < 4; ++d0) { const float v = MODE == 0 ? o[d0][r] * rli[r] : o[d0][r];
;                 const float vn = __shfl_xor(v, 1);
;                 if ((r32 & 1) == 0 && wid * 32 + orow < D.nq) *(unsigned*)(Ow + (size_t)orow * DM + d0 * 32 + r32) = cvt_pk_bf16(v, vn); } }
.LBB0_1871:
	s_or_b64 exec, exec, s[10:11]
	s_waitcnt lgkmcnt(0)
	s_nop 1
	v_mov_b32_dpp v4, v61 quad_perm:[1,0,3,2] row_mask:0xf bank_mask:0xf
	v_or_b32_e32 v2, 19, v179
	v_or_b32_e32 v5, s8, v2
	v_lshlrev_b32_e32 v162, 12, v2
	v_cmp_gt_i32_e64 s[10:11], s6, v5
	v_lshl_add_u64 v[2:3], v[66:67], 0, v[162:163]
	s_and_b64 s[4:5], vcc, s[10:11]
	s_and_saveexec_b64 s[10:11], s[4:5]
	s_cbranch_execz .LBB0_1873
	s_waitcnt lgkmcnt(0)
	v_cvt_pk_bf16_f32 v4, v61, v4
	global_store_dword v[2:3], v4, off

; __device__ __forceinline__ unsigned cvt_pk_bf16(float lo, float hi) { unsigned r; asm volatile("v_cvt_pk_bf16_f32 %0, %1, %2" : "=v"(r) : "v"(lo), "v"(hi)); return r; }
; __device__ __forceinline__ int crow(int r, int hi) { return (r & 3) + 8 * (r >> 2) + 4 * hi; }
; template <int MODE, bool SAMPLE>
; __device__ __forceinline__ void unit(LAS char* lds, const UnitDesc& D) {
;     ...
;         bf16* Ow = D.O + (size_t)(wid * 32) * DM;
; #pragma unroll
;         for (int r = 0; r < 16; ++r) { const int orow = crow(r, hi);
; #pragma unroll
;             for (int d0 = 0; d0 < 4; ++d0) { const float v = MODE == 0 ? o[d0][r] * rli[r] : o[d0][r];
;                 const float vn = __shfl_xor(v, 1);
;                 if ((r32 & 1) == 0 && wid * 32 + orow < D.nq) *(unsigned*)(Ow + (size_t)orow * DM + d0 * 32 + r32) = cvt_pk_bf16(v, vn); } }
.LBB0_1879:
	s_or_b64 exec, exec, s[10:11]
	s_waitcnt lgkmcnt(0)
	s_nop 1
	v_mov_b32_dpp v4, v62 quad_perm:[1,0,3,2] row_mask:0xf bank_mask:0xf
	v_or_b32_e32 v2, 24, v179
	v_or_b32_e32 v5, s8, v2
	v_lshlrev_b32_e32 v162, 12, v2
	v_cmp_gt_i32_e64 s[10:11], s6, v5
	v_lshl_add_u64 v[2:3], v[66:67], 0, v[162:163]
	s_and_b64 s[4:5], vcc, s[10:11]
	s_and_saveexec_b64 s[10:11], s[4:5]
	s_cbranch_execz .LBB0_1881
	s_waitcnt lgkmcnt(0)
	v_cvt_pk_bf16_f32 v4, v62, v4
	global_store_dword v[2:3], v4, off

; __device__ __forceinline__ unsigned cvt_pk_bf16(float lo, float hi) { unsigned r; asm volatile("v_cvt_pk_bf16_f32 %0, %1, %2" : "=v"(r) : "v"(lo), "v"(hi)); return r; }
; __device__ __forceinline__ int crow(int r, int hi) { return (r & 3) + 8 * (r >> 2) + 4 * hi; }
; template <int MODE, bool SAMPLE>
; __device__ __forceinline__ void unit(LAS char* lds, const UnitDesc& D) {
;     ...
;         bf16* Ow = D.O + (size_t)(wid * 32) * DM;
; #pragma unroll
;         for (int r = 0; r < 16; ++r) { const int orow = crow(r, hi);
; #pragma unroll
;             for (int d0 = 0; d0 < 4; ++d0) { const float v = MODE == 0 ? o[d0][r] * rli[r] : o[d0][r];
;                 const float vn = __shfl_xor(v, 1);
;                 if ((r32 & 1) == 0 && wid * 32 + orow < D.nq) *(unsigned*)(Ow + (size_t)orow * DM + d0 * 32 + r32) = cvt_pk_bf16(v, vn); } }
.LBB0_1887:
	s_or_b64 exec, exec, s[10:11]
	s_waitcnt lgkmcnt(0)
	s_nop 1
	v_mov_b32_dpp v4, v63 quad_perm:[1,0,3,2] row_mask:0xf bank_mask:0xf
	v_or_b32_e32 v2, 25, v179
	v_or_b32_e32 v5, s8, v2
	v_lshlrev_b32_e32 v162, 12, v2
	v_cmp_gt_i32_e64 s[10:11], s6, v5
	v_lshl_add_u64 v[2:3], v[66:67], 0, v[162:163]
	s_and_b64 s[4:5], vcc, s[10:11]
	s_and_saveexec_b64 s[10:11], s[4:5]
	s_cbranch_execz .LBB0_1889
	s_waitcnt lgkmcnt(0)
	v_cvt_pk_bf16_f32 v4, v63, v4
	global_store_dword v[2:3], v4, off

; __device__ __forceinline__ unsigned cvt_pk_bf16(float lo, float hi) { unsigned r; asm volatile("v_cvt_pk_bf16_f32 %0, %1, %2" : "=v"(r) : "v"(lo), "v"(hi)); return r; }
; __device__ __forceinline__ int crow(int r, int hi) { return (r & 3) + 8 * (r >> 2) + 4 * hi; }
; template <int MODE, bool SAMPLE>
; __device__ __forceinline__ void unit(LAS char* lds, const UnitDesc& D) {
;     ...
;         bf16* Ow = D.O + (size_t)(wid * 32) * DM;
; #pragma unroll
;         for (int r = 0; r < 16; ++r) { const int orow = crow(r, hi);
; #pragma unroll
;             for (int d0 = 0; d0 < 4; ++d0) { const float v = MODE == 0 ? o[d0][r] * rli[r] : o[d0][r];
;                 const float vn = __shfl_xor(v, 1);
;                 if ((r32 & 1) == 0 && wid * 32 + orow < D.nq) *(unsigned*)(Ow + (size_t)orow * DM + d0 * 32 + r32) = cvt_pk_bf16(v, vn); } }
.LBB0_1895:
	s_or_b64 exec, exec, s[10:11]
	s_waitcnt lgkmcnt(0)
	s_nop 1
	v_mov_b32_dpp v4, v64 quad_perm:[1,0,3,2] row_mask:0xf bank_mask:0xf
	v_or_b32_e32 v2, 26, v179
	v_or_b32_e32 v5, s8, v2
	v_lshlrev_b32_e32 v162, 12, v2
	v_cmp_gt_i32_e64 s[10:11], s6, v5
	v_lshl_add_u64 v[2:3], v[66:67], 0, v[162:163]
	s_and_b64 s[4:5], vcc, s[10:11]
	s_and_saveexec_b64 s[10:11], s[4:5]
	s_cbranch_execz .LBB0_1897
	s_waitcnt lgkmcnt(0)
	v_cvt_pk_bf16_f32 v4, v64, v4
	global_store_dword v[2:3], v4, off

; __device__ __forceinline__ unsigned cvt_pk_bf16(float lo, float hi) { unsigned r; asm volatile("v_cvt_pk_bf16_f32 %0, %1, %2" : "=v"(r) : "v"(lo), "v"(hi)); return r; }
; __device__ __forceinline__ int crow(int r, int hi) { return (r & 3) + 8 * (r >> 2) + 4 * hi; }
; template <int MODE, bool SAMPLE>
; __device__ __forceinline__ void unit(LAS char* lds, const UnitDesc& D) {
;     ...
;         bf16* Ow = D.O + (size_t)(wid * 32) * DM;
; #pragma unroll
;         for (int r = 0; r < 16; ++r) { const int orow = crow(r, hi);
; #pragma unroll
;             for (int d0 = 0; d0 < 4; ++d0) { const float v = MODE == 0 ? o[d0][r] * rli[r] : o[d0][r];
;                 const float vn = __shfl_xor(v, 1);
;                 if ((r32 & 1) == 0 && wid * 32 + orow < D.nq) *(unsigned*)(Ow + (size_t)orow * DM + d0 * 32 + r32) = cvt_pk_bf16(v, vn); } }
.LBB0_1903:
	s_or_b64 exec, exec, s[10:11]
	s_waitcnt lgkmcnt(0)
	s_nop 1
	v_mov_b32_dpp v4, v65 quad_perm:[1,0,3,2] row_mask:0xf bank_mask:0xf
	v_or_b32_e32 v2, 27, v179
	v_or_b32_e32 v5, s8, v2
	v_lshlrev_b32_e32 v162, 12, v2
	v_cmp_gt_i32_e64 s[10:11], s6, v5
	v_lshl_add_u64 v[2:3], v[66:67], 0, v[162:163]
	s_and_b64 s[4:5], vcc, s[10:11]
	s_and_saveexec_b64 s[8:9], s[4:5]
	s_cbranch_execz .LBB0_1905
	s_waitcnt lgkmcnt(0)
	v_cvt_pk_bf16_f32 v4, v65, v4
	global_store_dword v[2:3], v4, off

; __device__ __forceinline__ unsigned cvt_pk_bf16(float lo, float hi) { unsigned r; asm volatile("v_cvt_pk_bf16_f32 %0, %1, %2" : "=v"(r) : "v"(lo), "v"(hi)); return r; }
; __device__ __forceinline__ int crow(int r, int hi) { return (r & 3) + 8 * (r >> 2) + 4 * hi; }
; template <int MODE, bool SAMPLE>
; __device__ __forceinline__ void unit(LAS char* lds, const UnitDesc& D) {
;     ...
;         bf16* Ow = D.O + (size_t)(wid * 32) * DM;
; #pragma unroll
;         for (int r = 0; r < 16; ++r) { const int orow = crow(r, hi);
; #pragma unroll
;             for (int d0 = 0; d0 < 4; ++d0) { const float v = MODE == 0 ? o[d0][r] * rli[r] : o[d0][r];
;                 const float vn = __shfl_xor(v, 1);
;                 if ((r32 & 1) == 0 && wid * 32 + orow < D.nq) *(unsigned*)(Ow + (size_t)orow * DM + d0 * 32 + r32) = cvt_pk_bf16(v, vn); } }
.LBB0_1909:
	s_or_b64 exec, exec, s[8:9]
	s_waitcnt lgkmcnt(0)
	s_nop 1
	v_mov_b32_dpp v4, v17 quad_perm:[1,0,3,2] row_mask:0xf bank_mask:0xf
	s_and_saveexec_b64 s[8:9], s[4:5]
	s_cbranch_execz .LBB0_1608
	s_waitcnt lgkmcnt(0)
	v_cvt_pk_bf16_f32 v4, v17, v4
	global_store_dword v[2:3], v4, off offset:192
	s_branch .LBB0_1608
